# GEMM tiles: accumulator zeroing moved into the first load phase of the K-loop's first iteration (after LDS reads are issued), one-shot flag
# baseline (speedup 1.0000x reference)
.LBB0_343:
	s_ashr_i32 s11, s10, 31
	s_lshl_b64 s[16:17], s[10:11], 19
	s_add_u32 s16, s68, s16
	s_addc_u32 s17, s69, s17
	s_and_b64 s[18:19], s[0:1], exec
	s_cselect_b32 s11, s17, s25
	s_cselect_b32 s21, s16, s24
	s_ashr_i32 s9, s8, 31
	s_lshl_b64 s[18:19], s[8:9], 19
	s_add_u32 s18, s2, s18
	s_addc_u32 s19, s3, s19
	s_and_b64 s[28:29], s[0:1], exec
	s_cselect_b32 s9, s19, s27
	s_cselect_b32 s41, s18, s26
	s_add_u32 s24, s24, 0x40080
	s_addc_u32 s25, s25, 0
	s_add_u32 s42, s26, 0x100
	v_mov_b32_e32 v0, 0
	s_addc_u32 s43, s27, 0
	s_mov_b32 s44, -2
	s_mov_b32 s96, 1
.LBB0_344:
	ds_read_b128 v[144:147], v149
	ds_read_b128 v[152:155], v149 offset:1024
	ds_read_b128 v[156:159], v149 offset:2048
	ds_read_b128 v[160:163], v149 offset:3072
	ds_read_b128 v[164:167], v150
	ds_read_b128 v[168:171], v150 offset:1024
	ds_read_b128 v[172:175], v150 offset:2048
	ds_read_b128 v[176:179], v150 offset:3072
	s_add_u32 s26, s24, 0xfffc0080
	s_addc_u32 s27, s25, -1
	s_cmp_eq_u32 s44, 12
	s_cselect_b32 s29, s11, s27
	s_cselect_b32 s28, s21, s26
	s_cselect_b32 s27, s9, s43
	s_cselect_b32 s26, s41, s42
	v_lshl_add_u64 v[212:213], s[24:25], 0, v[136:137]
	s_add_i32 m0, s23, 0xc000
	ds_read_b128 v[180:183], v151
	ds_read_b128 v[184:187], v151 offset:1024
	ds_read_b128 v[188:191], v151 offset:2048
	ds_read_b128 v[192:195], v151 offset:3072
	ds_read_b128 v[196:199], v151 offset:4096
	ds_read_b128 v[200:203], v151 offset:5120
	ds_read_b128 v[204:207], v151 offset:6144
	ds_read_b128 v[208:211], v151 offset:7168
	global_load_lds_dwordx4 v[212:213], off
	v_lshl_add_u64 v[212:213], s[24:25], 0, v[138:139]
	s_add_i32 m0, s23, 0xe000
	s_nop 0
	global_load_lds_dwordx4 v[212:213], off
	s_cmp_lg_u32 s96, 0
	s_cbranch_scc0 .Lz_skip_5
	s_mov_b32 s96, 0
	v_mov_b64_e32 v[0:1], 0
	v_mov_b64_e32 v[2:3], 0
	v_mov_b64_e32 v[4:5], 0
	v_mov_b64_e32 v[6:7], 0
	v_mov_b64_e32 v[8:9], 0
	v_mov_b64_e32 v[10:11], 0
	v_mov_b64_e32 v[12:13], 0
	v_mov_b64_e32 v[14:15], 0
	v_mov_b64_e32 v[16:17], 0
	v_mov_b64_e32 v[18:19], 0
	v_mov_b64_e32 v[20:21], 0
	v_mov_b64_e32 v[22:23], 0
	v_mov_b64_e32 v[24:25], 0
	v_mov_b64_e32 v[26:27], 0
	v_mov_b64_e32 v[28:29], 0
	v_mov_b64_e32 v[30:31], 0
	v_mov_b64_e32 v[32:33], 0
	v_mov_b64_e32 v[34:35], 0
	v_mov_b64_e32 v[36:37], 0
	v_mov_b64_e32 v[38:39], 0
	v_mov_b64_e32 v[40:41], 0
	v_mov_b64_e32 v[42:43], 0
	v_mov_b64_e32 v[44:45], 0
	v_mov_b64_e32 v[46:47], 0
	v_mov_b64_e32 v[48:49], 0
	v_mov_b64_e32 v[50:51], 0
	v_mov_b64_e32 v[52:53], 0
	v_mov_b64_e32 v[54:55], 0
	v_mov_b64_e32 v[56:57], 0
	v_mov_b64_e32 v[58:59], 0
	v_mov_b64_e32 v[60:61], 0
	v_mov_b64_e32 v[62:63], 0
	v_mov_b64_e32 v[64:65], 0
	v_mov_b64_e32 v[66:67], 0
	v_mov_b64_e32 v[68:69], 0
	v_mov_b64_e32 v[70:71], 0
	v_mov_b64_e32 v[72:73], 0
	v_mov_b64_e32 v[74:75], 0
	v_mov_b64_e32 v[76:77], 0
	v_mov_b64_e32 v[78:79], 0
	v_mov_b64_e32 v[80:81], 0
	v_mov_b64_e32 v[82:83], 0
	v_mov_b64_e32 v[84:85], 0
	v_mov_b64_e32 v[86:87], 0
	v_mov_b64_e32 v[88:89], 0
	v_mov_b64_e32 v[90:91], 0
	v_mov_b64_e32 v[92:93], 0
	v_mov_b64_e32 v[94:95], 0
	v_mov_b64_e32 v[96:97], 0
	v_mov_b64_e32 v[98:99], 0
	v_mov_b64_e32 v[100:101], 0
	v_mov_b64_e32 v[102:103], 0
	v_mov_b64_e32 v[104:105], 0
	v_mov_b64_e32 v[106:107], 0
	v_mov_b64_e32 v[108:109], 0
	v_mov_b64_e32 v[110:111], 0
	v_mov_b64_e32 v[112:113], 0
	v_mov_b64_e32 v[114:115], 0
	v_mov_b64_e32 v[116:117], 0
	v_mov_b64_e32 v[118:119], 0
	v_mov_b64_e32 v[120:121], 0
	v_mov_b64_e32 v[122:123], 0
	v_mov_b64_e32 v[124:125], 0
	v_mov_b64_e32 v[126:127], 0
.Lz_skip_5:
	s_waitcnt vmcnt(8)
	s_waitcnt lgkmcnt(0)
	s_barrier
	s_setprio 1
	s_waitcnt lgkmcnt(0)
	v_mfma_f32_16x16x32_bf16 v[124:127], v[144:147], v[180:183], v[124:127]
	v_mfma_f32_16x16x32_bf16 v[120:123], v[156:159], v[180:183], v[120:123]
	v_mfma_f32_16x16x32_bf16 v[116:119], v[144:147], v[188:191], v[116:119]
	v_mfma_f32_16x16x32_bf16 v[108:111], v[156:159], v[188:191], v[108:111]
	v_mfma_f32_16x16x32_bf16 v[100:103], v[144:147], v[196:199], v[100:103]
	v_mfma_f32_16x16x32_bf16 v[92:95], v[156:159], v[196:199], v[92:95]
	v_mfma_f32_16x16x32_bf16 v[84:87], v[144:147], v[204:207], v[84:87]
	v_mfma_f32_16x16x32_bf16 v[76:79], v[156:159], v[204:207], v[76:79]
	v_mfma_f32_16x16x32_bf16 v[124:127], v[152:155], v[184:187], v[124:127]
	v_mfma_f32_16x16x32_bf16 v[120:123], v[160:163], v[184:187], v[120:123]
	v_mfma_f32_16x16x32_bf16 v[116:119], v[152:155], v[192:195], v[116:119]
	v_mfma_f32_16x16x32_bf16 v[108:111], v[160:163], v[192:195], v[108:111]
	v_mfma_f32_16x16x32_bf16 v[100:103], v[152:155], v[200:203], v[100:103]
	v_mfma_f32_16x16x32_bf16 v[92:95], v[160:163], v[200:203], v[92:95]
	v_mfma_f32_16x16x32_bf16 v[84:87], v[152:155], v[208:211], v[84:87]
	v_mfma_f32_16x16x32_bf16 v[76:79], v[160:163], v[208:211], v[76:79]
	s_setprio 0
	s_setprio 1
	v_mfma_f32_16x16x32_bf16 v[112:115], v[164:167], v[180:183], v[112:115]
	v_mfma_f32_16x16x32_bf16 v[104:107], v[172:175], v[180:183], v[104:107]
	v_mfma_f32_16x16x32_bf16 v[96:99], v[164:167], v[188:191], v[96:99]
	v_mfma_f32_16x16x32_bf16 v[88:91], v[172:175], v[188:191], v[88:91]
	v_mfma_f32_16x16x32_bf16 v[80:83], v[164:167], v[196:199], v[80:83]
	v_mfma_f32_16x16x32_bf16 v[72:75], v[172:175], v[196:199], v[72:75]
	v_mfma_f32_16x16x32_bf16 v[68:71], v[164:167], v[204:207], v[68:71]
	v_mfma_f32_16x16x32_bf16 v[64:67], v[172:175], v[204:207], v[64:67]
	v_mfma_f32_16x16x32_bf16 v[112:115], v[168:171], v[184:187], v[112:115]
	v_mfma_f32_16x16x32_bf16 v[104:107], v[176:179], v[184:187], v[104:107]
	v_mfma_f32_16x16x32_bf16 v[96:99], v[168:171], v[192:195], v[96:99]
	v_mfma_f32_16x16x32_bf16 v[88:91], v[176:179], v[192:195], v[88:91]
	v_mfma_f32_16x16x32_bf16 v[80:83], v[168:171], v[200:203], v[80:83]
	v_mfma_f32_16x16x32_bf16 v[72:75], v[176:179], v[200:203], v[72:75]
	v_mfma_f32_16x16x32_bf16 v[68:71], v[168:171], v[208:211], v[68:71]
	v_mfma_f32_16x16x32_bf16 v[64:67], v[176:179], v[208:211], v[64:67]
	s_setprio 0
	s_barrier
	s_add_i32 s45, s38, s33
	v_lshl_add_u64 v[212:213], s[26:27], 0, v[130:131]
	s_mov_b32 m0, s45
	ds_read_b128 v[180:183], v151 offset:16384
	ds_read_b128 v[184:187], v151 offset:17408
	ds_read_b128 v[188:191], v151 offset:18432
	ds_read_b128 v[192:195], v151 offset:19456
	ds_read_b128 v[196:199], v151 offset:20480
	ds_read_b128 v[200:203], v151 offset:21504
	ds_read_b128 v[204:207], v151 offset:22528
	ds_read_b128 v[208:211], v151 offset:23552
	global_load_lds_dwordx4 v[212:213], off
	s_add_i32 m0, s45, 0x2000
	s_add_u32 s46, s26, 0x40000
	v_lshl_add_u64 v[214:215], s[26:27], 0, v[134:135]
	s_addc_u32 s47, s27, 0
	s_add_i32 s45, s39, s33
	global_load_lds_dwordx4 v[214:215], off
	v_lshl_add_u64 v[216:217], s[46:47], 0, v[130:131]
	s_mov_b32 m0, s45
	v_lshl_add_u64 v[218:219], s[28:29], 0, v[132:133]
	global_load_lds_dwordx4 v[216:217], off
	v_lshl_add_u64 v[216:217], s[46:47], 0, v[134:135]
	s_add_i32 m0, s45, 0x2000
	s_nop 0
	global_load_lds_dwordx4 v[216:217], off
	v_lshl_add_u64 v[216:217], s[28:29], 0, v[128:129]
	s_mov_b32 m0, s23
	s_nop 0
	global_load_lds_dwordx4 v[216:217], off
	s_mov_b32 m0, s30
	s_nop 0
	global_load_lds_dwordx4 v[218:219], off
	s_waitcnt vmcnt(8)
	s_waitcnt lgkmcnt(0)
	s_barrier
	s_setprio 1
	s_waitcnt lgkmcnt(0)
	v_mfma_f32_16x16x32_bf16 v[60:63], v[144:147], v[180:183], v[60:63]
	v_mfma_f32_16x16x32_bf16 v[56:59], v[156:159], v[180:183], v[56:59]
	v_mfma_f32_16x16x32_bf16 v[52:55], v[144:147], v[188:191], v[52:55]
	v_mfma_f32_16x16x32_bf16 v[44:47], v[156:159], v[188:191], v[44:47]
	v_mfma_f32_16x16x32_bf16 v[36:39], v[144:147], v[196:199], v[36:39]
	v_mfma_f32_16x16x32_bf16 v[28:31], v[156:159], v[196:199], v[28:31]
	v_mfma_f32_16x16x32_bf16 v[20:23], v[144:147], v[204:207], v[20:23]
	v_mfma_f32_16x16x32_bf16 v[12:15], v[156:159], v[204:207], v[12:15]
	v_mfma_f32_16x16x32_bf16 v[60:63], v[152:155], v[184:187], v[60:63]
	v_mfma_f32_16x16x32_bf16 v[56:59], v[160:163], v[184:187], v[56:59]
	v_mfma_f32_16x16x32_bf16 v[52:55], v[152:155], v[192:195], v[52:55]
	v_mfma_f32_16x16x32_bf16 v[44:47], v[160:163], v[192:195], v[44:47]
	v_mfma_f32_16x16x32_bf16 v[36:39], v[152:155], v[200:203], v[36:39]
	v_mfma_f32_16x16x32_bf16 v[28:31], v[160:163], v[200:203], v[28:31]
	v_mfma_f32_16x16x32_bf16 v[20:23], v[152:155], v[208:211], v[20:23]
	v_mfma_f32_16x16x32_bf16 v[12:15], v[160:163], v[208:211], v[12:15]
	s_setprio 0
	s_setprio 1
	v_mfma_f32_16x16x32_bf16 v[48:51], v[164:167], v[180:183], v[48:51]
	v_mfma_f32_16x16x32_bf16 v[40:43], v[172:175], v[180:183], v[40:43]
	v_mfma_f32_16x16x32_bf16 v[32:35], v[164:167], v[188:191], v[32:35]
	v_mfma_f32_16x16x32_bf16 v[24:27], v[172:175], v[188:191], v[24:27]
	v_mfma_f32_16x16x32_bf16 v[16:19], v[164:167], v[196:199], v[16:19]
	v_mfma_f32_16x16x32_bf16 v[8:11], v[172:175], v[196:199], v[8:11]
	v_mfma_f32_16x16x32_bf16 v[4:7], v[164:167], v[204:207], v[4:7]
	v_mfma_f32_16x16x32_bf16 v[0:3], v[172:175], v[204:207], v[0:3]
	v_mfma_f32_16x16x32_bf16 v[48:51], v[168:171], v[184:187], v[48:51]
	v_mfma_f32_16x16x32_bf16 v[40:43], v[176:179], v[184:187], v[40:43]
	v_mfma_f32_16x16x32_bf16 v[32:35], v[168:171], v[192:195], v[32:35]
	v_mfma_f32_16x16x32_bf16 v[24:27], v[176:179], v[192:195], v[24:27]
	v_mfma_f32_16x16x32_bf16 v[16:19], v[168:171], v[200:203], v[16:19]
	v_mfma_f32_16x16x32_bf16 v[8:11], v[176:179], v[200:203], v[8:11]
	v_mfma_f32_16x16x32_bf16 v[4:7], v[168:171], v[208:211], v[4:7]
	v_mfma_f32_16x16x32_bf16 v[0:3], v[176:179], v[208:211], v[0:3]
	s_setprio 0
	s_barrier
	s_add_i32 s45, 0, 0x18000
	s_add_i32 s46, 0, 0x1c000
	v_add_u32_e32 v160, s45, v148
	v_add_u32_e32 v176, s46, v148
	ds_read_b128 v[144:147], v160
	ds_read_b128 v[152:155], v160 offset:1024
	ds_read_b128 v[156:159], v160 offset:2048
	ds_read_b128 v[160:163], v160 offset:3072
	ds_read_b128 v[164:167], v176
	ds_read_b128 v[168:171], v176 offset:1024
	ds_read_b128 v[172:175], v176 offset:2048
	ds_read_b128 v[176:179], v176 offset:3072
	s_add_u32 s28, s28, 0x40000
	s_addc_u32 s29, s29, 0
	s_mov_b32 m0, s31
	v_lshl_add_u64 v[220:221], s[28:29], 0, v[128:129]
	ds_read_b128 v[180:183], v151 offset:32768
	ds_read_b128 v[184:187], v151 offset:33792
	ds_read_b128 v[188:191], v151 offset:34816
	ds_read_b128 v[192:195], v151 offset:35840
	ds_read_b128 v[196:199], v151 offset:36864
	ds_read_b128 v[200:203], v151 offset:37888
	ds_read_b128 v[204:207], v151 offset:38912
	ds_read_b128 v[208:211], v151 offset:39936
	global_load_lds_dwordx4 v[220:221], off
	v_lshl_add_u64 v[220:221], s[28:29], 0, v[132:133]
	s_mov_b32 m0, s34
	s_nop 0
	global_load_lds_dwordx4 v[220:221], off
	s_waitcnt vmcnt(8)
	s_waitcnt lgkmcnt(0)
	s_barrier
	s_setprio 1
	s_waitcnt lgkmcnt(0)
	v_mfma_f32_16x16x32_bf16 v[124:127], v[144:147], v[180:183], v[124:127]
	v_mfma_f32_16x16x32_bf16 v[120:123], v[156:159], v[180:183], v[120:123]
	v_mfma_f32_16x16x32_bf16 v[116:119], v[144:147], v[188:191], v[116:119]
	v_mfma_f32_16x16x32_bf16 v[108:111], v[156:159], v[188:191], v[108:111]
	v_mfma_f32_16x16x32_bf16 v[100:103], v[144:147], v[196:199], v[100:103]
	v_mfma_f32_16x16x32_bf16 v[92:95], v[156:159], v[196:199], v[92:95]
	v_mfma_f32_16x16x32_bf16 v[84:87], v[144:147], v[204:207], v[84:87]
	v_mfma_f32_16x16x32_bf16 v[76:79], v[156:159], v[204:207], v[76:79]
	v_mfma_f32_16x16x32_bf16 v[124:127], v[152:155], v[184:187], v[124:127]
	v_mfma_f32_16x16x32_bf16 v[120:123], v[160:163], v[184:187], v[120:123]
	v_mfma_f32_16x16x32_bf16 v[116:119], v[152:155], v[192:195], v[116:119]
	v_mfma_f32_16x16x32_bf16 v[108:111], v[160:163], v[192:195], v[108:111]
	v_mfma_f32_16x16x32_bf16 v[100:103], v[152:155], v[200:203], v[100:103]
	v_mfma_f32_16x16x32_bf16 v[92:95], v[160:163], v[200:203], v[92:95]
	v_mfma_f32_16x16x32_bf16 v[84:87], v[152:155], v[208:211], v[84:87]
	v_mfma_f32_16x16x32_bf16 v[76:79], v[160:163], v[208:211], v[76:79]
	s_setprio 0
	s_setprio 1
	v_mfma_f32_16x16x32_bf16 v[112:115], v[164:167], v[180:183], v[112:115]
	v_mfma_f32_16x16x32_bf16 v[104:107], v[172:175], v[180:183], v[104:107]
	v_mfma_f32_16x16x32_bf16 v[96:99], v[164:167], v[188:191], v[96:99]
	v_mfma_f32_16x16x32_bf16 v[88:91], v[172:175], v[188:191], v[88:91]
	v_mfma_f32_16x16x32_bf16 v[80:83], v[164:167], v[196:199], v[80:83]
	v_mfma_f32_16x16x32_bf16 v[72:75], v[172:175], v[196:199], v[72:75]
	v_mfma_f32_16x16x32_bf16 v[68:71], v[164:167], v[204:207], v[68:71]
	v_mfma_f32_16x16x32_bf16 v[64:67], v[172:175], v[204:207], v[64:67]
	v_mfma_f32_16x16x32_bf16 v[112:115], v[168:171], v[184:187], v[112:115]
	v_mfma_f32_16x16x32_bf16 v[104:107], v[176:179], v[184:187], v[104:107]
	v_mfma_f32_16x16x32_bf16 v[96:99], v[168:171], v[192:195], v[96:99]
	v_mfma_f32_16x16x32_bf16 v[88:91], v[176:179], v[192:195], v[88:91]
	v_mfma_f32_16x16x32_bf16 v[80:83], v[168:171], v[200:203], v[80:83]
	v_mfma_f32_16x16x32_bf16 v[72:75], v[176:179], v[200:203], v[72:75]
	v_mfma_f32_16x16x32_bf16 v[68:71], v[168:171], v[208:211], v[68:71]
	v_mfma_f32_16x16x32_bf16 v[64:67], v[176:179], v[208:211], v[64:67]
	s_setprio 0
	s_barrier
	s_add_i32 s28, s45, s33
	v_lshl_add_u64 v[212:213], v[212:213], 0, s[6:7]
	s_mov_b32 m0, s28
	ds_read_b128 v[180:183], v151 offset:49152
	ds_read_b128 v[184:187], v151 offset:50176
	ds_read_b128 v[188:191], v151 offset:51200
	ds_read_b128 v[192:195], v151 offset:52224
	ds_read_b128 v[196:199], v151 offset:53248
	ds_read_b128 v[200:203], v151 offset:54272
	ds_read_b128 v[204:207], v151 offset:55296
	ds_read_b128 v[208:211], v151 offset:56320
	global_load_lds_dwordx4 v[212:213], off
	s_add_i32 m0, s28, 0x2000
	s_add_u32 s26, s26, 0x40080
	v_lshl_add_u64 v[212:213], v[214:215], 0, s[6:7]
	s_addc_u32 s27, s27, 0
	s_add_i32 s28, s46, s33
	global_load_lds_dwordx4 v[212:213], off
	v_lshl_add_u64 v[212:213], s[26:27], 0, v[130:131]
	s_mov_b32 m0, s28
	s_nop 0
	global_load_lds_dwordx4 v[212:213], off
	v_lshl_add_u64 v[212:213], s[26:27], 0, v[134:135]
	s_add_i32 m0, s28, 0x2000
	s_nop 0
	global_load_lds_dwordx4 v[212:213], off
	v_lshl_add_u64 v[212:213], v[216:217], 0, s[6:7]
	s_mov_b32 m0, s36
	s_nop 0
	global_load_lds_dwordx4 v[212:213], off
	v_lshl_add_u64 v[212:213], v[218:219], 0, s[6:7]
	s_mov_b32 m0, s37
	s_nop 0
	global_load_lds_dwordx4 v[212:213], off
	s_waitcnt vmcnt(8)
	s_waitcnt lgkmcnt(0)
	s_barrier
	s_setprio 1
	s_waitcnt lgkmcnt(0)
	v_mfma_f32_16x16x32_bf16 v[60:63], v[144:147], v[180:183], v[60:63]
	v_mfma_f32_16x16x32_bf16 v[56:59], v[156:159], v[180:183], v[56:59]
	v_mfma_f32_16x16x32_bf16 v[52:55], v[144:147], v[188:191], v[52:55]
	v_mfma_f32_16x16x32_bf16 v[44:47], v[156:159], v[188:191], v[44:47]
	v_mfma_f32_16x16x32_bf16 v[36:39], v[144:147], v[196:199], v[36:39]
	v_mfma_f32_16x16x32_bf16 v[28:31], v[156:159], v[196:199], v[28:31]
	v_mfma_f32_16x16x32_bf16 v[20:23], v[144:147], v[204:207], v[20:23]
	v_mfma_f32_16x16x32_bf16 v[12:15], v[156:159], v[204:207], v[12:15]
	v_mfma_f32_16x16x32_bf16 v[60:63], v[152:155], v[184:187], v[60:63]
	v_mfma_f32_16x16x32_bf16 v[56:59], v[160:163], v[184:187], v[56:59]
	v_mfma_f32_16x16x32_bf16 v[52:55], v[152:155], v[192:195], v[52:55]
	v_mfma_f32_16x16x32_bf16 v[44:47], v[160:163], v[192:195], v[44:47]
	v_mfma_f32_16x16x32_bf16 v[36:39], v[152:155], v[200:203], v[36:39]
	v_mfma_f32_16x16x32_bf16 v[28:31], v[160:163], v[200:203], v[28:31]
	v_mfma_f32_16x16x32_bf16 v[20:23], v[152:155], v[208:211], v[20:23]
	v_mfma_f32_16x16x32_bf16 v[12:15], v[160:163], v[208:211], v[12:15]
	s_setprio 0
	s_setprio 1
	v_mfma_f32_16x16x32_bf16 v[48:51], v[164:167], v[180:183], v[48:51]
	v_mfma_f32_16x16x32_bf16 v[40:43], v[172:175], v[180:183], v[40:43]
	v_mfma_f32_16x16x32_bf16 v[32:35], v[164:167], v[188:191], v[32:35]
	v_mfma_f32_16x16x32_bf16 v[24:27], v[172:175], v[188:191], v[24:27]
	v_mfma_f32_16x16x32_bf16 v[16:19], v[164:167], v[196:199], v[16:19]
	v_mfma_f32_16x16x32_bf16 v[8:11], v[172:175], v[196:199], v[8:11]
	v_mfma_f32_16x16x32_bf16 v[4:7], v[164:167], v[204:207], v[4:7]
	v_mfma_f32_16x16x32_bf16 v[0:3], v[172:175], v[204:207], v[0:3]
	v_mfma_f32_16x16x32_bf16 v[48:51], v[168:171], v[184:187], v[48:51]
	v_mfma_f32_16x16x32_bf16 v[40:43], v[176:179], v[184:187], v[40:43]
	v_mfma_f32_16x16x32_bf16 v[32:35], v[168:171], v[192:195], v[32:35]
	v_mfma_f32_16x16x32_bf16 v[24:27], v[176:179], v[192:195], v[24:27]
	v_mfma_f32_16x16x32_bf16 v[16:19], v[168:171], v[200:203], v[16:19]
	v_mfma_f32_16x16x32_bf16 v[8:11], v[176:179], v[200:203], v[8:11]
	v_mfma_f32_16x16x32_bf16 v[4:7], v[168:171], v[208:211], v[4:7]
	v_mfma_f32_16x16x32_bf16 v[0:3], v[176:179], v[208:211], v[0:3]
	s_setprio 0
	s_barrier
	s_add_i32 s44, s44, 2
	s_add_u32 s24, s24, 0x100
	s_addc_u32 s25, s25, 0
	s_add_u32 s42, s42, 0x100
	s_addc_u32 s43, s43, 0
	s_cmp_gt_u32 s44, 13
	s_cbranch_scc0 .LBB0_344
	v_readlane_b32 s24, v255, 4
	v_readlane_b32 s25, v255, 5
	s_and_b64 vcc, exec, s[24:25]
	s_cbranch_vccz .LBB0_347
	s_barrier

.LBB0_928:
	s_ashr_i32 s15, s14, 31
	s_lshl_b64 s[16:17], s[14:15], 19
	s_add_u32 s16, s88, s16
	s_addc_u32 s17, s89, s17
	s_and_b64 s[18:19], s[0:1], exec
	s_cselect_b32 s15, s17, s23
	s_cselect_b32 s39, s16, s22
	s_ashr_i32 s13, s12, 31
	s_lshl_b64 s[18:19], s[12:13], 19
	v_readlane_b32 s26, v254, 27
	v_readlane_b32 s27, v254, 28
	s_add_u32 s18, s26, s18
	s_addc_u32 s19, s27, s19
	s_and_b64 s[26:27], s[0:1], exec
	s_cselect_b32 s13, s19, s25
	s_cselect_b32 s40, s18, s24
	s_add_u32 s22, s22, 0x40080
	s_addc_u32 s23, s23, 0
	s_add_u32 s41, s24, 0x100
	v_mov_b32_e32 v0, 0
	s_addc_u32 s42, s25, 0
	s_mov_b32 s43, -2
	s_mov_b32 s96, 1
.LBB0_929:
	ds_read_b128 v[128:131], v167
	ds_read_b128 v[132:135], v167 offset:1024
	ds_read_b128 v[136:139], v167 offset:2048
	ds_read_b128 v[140:143], v167 offset:3072
	ds_read_b128 v[160:163], v168
	ds_read_b128 v[170:173], v168 offset:1024
	ds_read_b128 v[174:177], v168 offset:2048
	ds_read_b128 v[178:181], v168 offset:3072
	s_add_u32 s24, s22, 0xfffc0080
	s_addc_u32 s25, s23, -1
	s_cmp_eq_u32 s43, 12
	s_cselect_b32 s27, s15, s25
	s_cselect_b32 s26, s39, s24
	s_cselect_b32 s25, s13, s42
	s_cselect_b32 s24, s40, s41
	v_lshl_add_u64 v[164:165], s[22:23], 0, v[152:153]
	s_add_i32 m0, s21, 0xc000
	ds_read_b128 v[182:185], v169
	ds_read_b128 v[186:189], v169 offset:1024
	ds_read_b128 v[190:193], v169 offset:2048
	ds_read_b128 v[194:197], v169 offset:3072
	ds_read_b128 v[198:201], v169 offset:4096
	ds_read_b128 v[202:205], v169 offset:5120
	ds_read_b128 v[206:209], v169 offset:6144
	ds_read_b128 v[210:213], v169 offset:7168
	global_load_lds_dwordx4 v[164:165], off
	v_lshl_add_u64 v[164:165], s[22:23], 0, v[154:155]
	s_add_i32 m0, s21, 0xe000
	s_nop 0
	global_load_lds_dwordx4 v[164:165], off
	s_cmp_lg_u32 s96, 0
	s_cbranch_scc0 .Lz_skip_4
	s_mov_b32 s96, 0
	v_mov_b64_e32 v[0:1], 0
	v_mov_b64_e32 v[2:3], 0
	v_mov_b64_e32 v[4:5], 0
	v_mov_b64_e32 v[6:7], 0
	v_mov_b64_e32 v[8:9], 0
	v_mov_b64_e32 v[10:11], 0
	v_mov_b64_e32 v[12:13], 0
	v_mov_b64_e32 v[14:15], 0
	v_mov_b64_e32 v[16:17], 0
	v_mov_b64_e32 v[18:19], 0
	v_mov_b64_e32 v[20:21], 0
	v_mov_b64_e32 v[22:23], 0
	v_mov_b64_e32 v[24:25], 0
	v_mov_b64_e32 v[26:27], 0
	v_mov_b64_e32 v[28:29], 0
	v_mov_b64_e32 v[30:31], 0
	v_mov_b64_e32 v[32:33], 0
	v_mov_b64_e32 v[34:35], 0
	v_mov_b64_e32 v[36:37], 0
	v_mov_b64_e32 v[38:39], 0
	v_mov_b64_e32 v[40:41], 0
	v_mov_b64_e32 v[42:43], 0
	v_mov_b64_e32 v[44:45], 0
	v_mov_b64_e32 v[46:47], 0
	v_mov_b64_e32 v[48:49], 0
	v_mov_b64_e32 v[50:51], 0
	v_mov_b64_e32 v[52:53], 0
	v_mov_b64_e32 v[54:55], 0
	v_mov_b64_e32 v[56:57], 0
	v_mov_b64_e32 v[58:59], 0
	v_mov_b64_e32 v[60:61], 0
	v_mov_b64_e32 v[62:63], 0
	v_mov_b64_e32 v[64:65], 0
	v_mov_b64_e32 v[66:67], 0
	v_mov_b64_e32 v[68:69], 0
	v_mov_b64_e32 v[70:71], 0
	v_mov_b64_e32 v[72:73], 0
	v_mov_b64_e32 v[74:75], 0
	v_mov_b64_e32 v[76:77], 0
	v_mov_b64_e32 v[78:79], 0
	v_mov_b64_e32 v[80:81], 0
	v_mov_b64_e32 v[82:83], 0
	v_mov_b64_e32 v[84:85], 0
	v_mov_b64_e32 v[86:87], 0
	v_mov_b64_e32 v[88:89], 0
	v_mov_b64_e32 v[90:91], 0
	v_mov_b64_e32 v[92:93], 0
	v_mov_b64_e32 v[94:95], 0
	v_mov_b64_e32 v[96:97], 0
	v_mov_b64_e32 v[98:99], 0
	v_mov_b64_e32 v[100:101], 0
	v_mov_b64_e32 v[102:103], 0
	v_mov_b64_e32 v[104:105], 0
	v_mov_b64_e32 v[106:107], 0
	v_mov_b64_e32 v[108:109], 0
	v_mov_b64_e32 v[110:111], 0
	v_mov_b64_e32 v[112:113], 0
	v_mov_b64_e32 v[114:115], 0
	v_mov_b64_e32 v[116:117], 0
	v_mov_b64_e32 v[118:119], 0
	v_mov_b64_e32 v[120:121], 0
	v_mov_b64_e32 v[122:123], 0
	v_mov_b64_e32 v[124:125], 0
	v_mov_b64_e32 v[126:127], 0
.Lz_skip_4:
	s_waitcnt vmcnt(8)
	s_waitcnt lgkmcnt(0)
	s_barrier
	s_setprio 1
	s_waitcnt lgkmcnt(0)
	v_mfma_f32_16x16x32_bf16 v[124:127], v[128:131], v[182:185], v[124:127]
	v_mfma_f32_16x16x32_bf16 v[120:123], v[136:139], v[182:185], v[120:123]
	v_mfma_f32_16x16x32_bf16 v[116:119], v[128:131], v[190:193], v[116:119]
	v_mfma_f32_16x16x32_bf16 v[112:115], v[136:139], v[190:193], v[112:115]
	v_mfma_f32_16x16x32_bf16 v[108:111], v[128:131], v[198:201], v[108:111]
	v_mfma_f32_16x16x32_bf16 v[96:99], v[136:139], v[198:201], v[96:99]
	v_mfma_f32_16x16x32_bf16 v[80:83], v[128:131], v[206:209], v[80:83]
	v_mfma_f32_16x16x32_bf16 v[76:79], v[136:139], v[206:209], v[76:79]
	v_mfma_f32_16x16x32_bf16 v[124:127], v[132:135], v[186:189], v[124:127]
	v_mfma_f32_16x16x32_bf16 v[120:123], v[140:143], v[186:189], v[120:123]
	v_mfma_f32_16x16x32_bf16 v[116:119], v[132:135], v[194:197], v[116:119]
	v_mfma_f32_16x16x32_bf16 v[112:115], v[140:143], v[194:197], v[112:115]
	v_mfma_f32_16x16x32_bf16 v[108:111], v[132:135], v[202:205], v[108:111]
	v_mfma_f32_16x16x32_bf16 v[96:99], v[140:143], v[202:205], v[96:99]
	v_mfma_f32_16x16x32_bf16 v[80:83], v[132:135], v[210:213], v[80:83]
	v_mfma_f32_16x16x32_bf16 v[76:79], v[140:143], v[210:213], v[76:79]
	s_setprio 0
	s_setprio 1
	v_mfma_f32_16x16x32_bf16 v[104:107], v[160:163], v[182:185], v[104:107]
	v_mfma_f32_16x16x32_bf16 v[100:103], v[174:177], v[182:185], v[100:103]
	v_mfma_f32_16x16x32_bf16 v[92:95], v[160:163], v[190:193], v[92:95]
	v_mfma_f32_16x16x32_bf16 v[88:91], v[174:177], v[190:193], v[88:91]
	v_mfma_f32_16x16x32_bf16 v[84:87], v[160:163], v[198:201], v[84:87]
	v_mfma_f32_16x16x32_bf16 v[72:75], v[174:177], v[198:201], v[72:75]
	v_mfma_f32_16x16x32_bf16 v[68:71], v[160:163], v[206:209], v[68:71]
	v_mfma_f32_16x16x32_bf16 v[64:67], v[174:177], v[206:209], v[64:67]
	v_mfma_f32_16x16x32_bf16 v[104:107], v[170:173], v[186:189], v[104:107]
	v_mfma_f32_16x16x32_bf16 v[100:103], v[178:181], v[186:189], v[100:103]
	v_mfma_f32_16x16x32_bf16 v[92:95], v[170:173], v[194:197], v[92:95]
	v_mfma_f32_16x16x32_bf16 v[88:91], v[178:181], v[194:197], v[88:91]
	v_mfma_f32_16x16x32_bf16 v[84:87], v[170:173], v[202:205], v[84:87]
	v_mfma_f32_16x16x32_bf16 v[72:75], v[178:181], v[202:205], v[72:75]
	v_mfma_f32_16x16x32_bf16 v[68:71], v[170:173], v[210:213], v[68:71]
	v_mfma_f32_16x16x32_bf16 v[64:67], v[178:181], v[210:213], v[64:67]
	s_setprio 0
	s_barrier
	s_add_i32 s44, s36, s33
	v_lshl_add_u64 v[164:165], s[24:25], 0, v[148:149]
	s_mov_b32 m0, s44
	ds_read_b128 v[182:185], v169 offset:16384
	ds_read_b128 v[186:189], v169 offset:17408
	ds_read_b128 v[190:193], v169 offset:18432
	ds_read_b128 v[194:197], v169 offset:19456
	ds_read_b128 v[198:201], v169 offset:20480
	ds_read_b128 v[202:205], v169 offset:21504
	ds_read_b128 v[206:209], v169 offset:22528
	ds_read_b128 v[210:213], v169 offset:23552
	global_load_lds_dwordx4 v[164:165], off
	s_add_i32 m0, s44, 0x2000
	s_add_u32 s44, s24, 0x40000
	v_lshl_add_u64 v[214:215], s[24:25], 0, v[144:145]
	s_addc_u32 s45, s25, 0
	s_add_i32 s48, s37, s33
	global_load_lds_dwordx4 v[214:215], off
	v_lshl_add_u64 v[216:217], s[44:45], 0, v[148:149]
	s_mov_b32 m0, s48
	v_lshl_add_u64 v[218:219], s[26:27], 0, v[146:147]
	global_load_lds_dwordx4 v[216:217], off
	v_lshl_add_u64 v[216:217], s[44:45], 0, v[144:145]
	s_add_i32 m0, s48, 0x2000
	s_nop 0
	global_load_lds_dwordx4 v[216:217], off
	v_lshl_add_u64 v[216:217], s[26:27], 0, v[150:151]
	s_mov_b32 m0, s21
	s_nop 0
	global_load_lds_dwordx4 v[216:217], off
	s_mov_b32 m0, s28
	s_nop 0
	global_load_lds_dwordx4 v[218:219], off
	s_waitcnt vmcnt(8)
	s_waitcnt lgkmcnt(0)
	s_barrier
	s_setprio 1
	s_waitcnt lgkmcnt(0)
	v_mfma_f32_16x16x32_bf16 v[60:63], v[128:131], v[182:185], v[60:63]
	v_mfma_f32_16x16x32_bf16 v[56:59], v[136:139], v[182:185], v[56:59]
	v_mfma_f32_16x16x32_bf16 v[52:55], v[128:131], v[190:193], v[52:55]
	v_mfma_f32_16x16x32_bf16 v[48:51], v[136:139], v[190:193], v[48:51]
	v_mfma_f32_16x16x32_bf16 v[44:47], v[128:131], v[198:201], v[44:47]
	v_mfma_f32_16x16x32_bf16 v[32:35], v[136:139], v[198:201], v[32:35]
	v_mfma_f32_16x16x32_bf16 v[16:19], v[128:131], v[206:209], v[16:19]
	v_mfma_f32_16x16x32_bf16 v[12:15], v[136:139], v[206:209], v[12:15]
	v_mfma_f32_16x16x32_bf16 v[60:63], v[132:135], v[186:189], v[60:63]
	v_mfma_f32_16x16x32_bf16 v[56:59], v[140:143], v[186:189], v[56:59]
	v_mfma_f32_16x16x32_bf16 v[52:55], v[132:135], v[194:197], v[52:55]
	v_mfma_f32_16x16x32_bf16 v[48:51], v[140:143], v[194:197], v[48:51]
	v_mfma_f32_16x16x32_bf16 v[44:47], v[132:135], v[202:205], v[44:47]
	v_mfma_f32_16x16x32_bf16 v[32:35], v[140:143], v[202:205], v[32:35]
	v_mfma_f32_16x16x32_bf16 v[16:19], v[132:135], v[210:213], v[16:19]
	v_mfma_f32_16x16x32_bf16 v[12:15], v[140:143], v[210:213], v[12:15]
	s_setprio 0
	s_setprio 1
	v_mfma_f32_16x16x32_bf16 v[40:43], v[160:163], v[182:185], v[40:43]
	v_mfma_f32_16x16x32_bf16 v[36:39], v[174:177], v[182:185], v[36:39]
	v_mfma_f32_16x16x32_bf16 v[28:31], v[160:163], v[190:193], v[28:31]
	v_mfma_f32_16x16x32_bf16 v[24:27], v[174:177], v[190:193], v[24:27]
	v_mfma_f32_16x16x32_bf16 v[20:23], v[160:163], v[198:201], v[20:23]
	v_mfma_f32_16x16x32_bf16 v[8:11], v[174:177], v[198:201], v[8:11]
	v_mfma_f32_16x16x32_bf16 v[4:7], v[160:163], v[206:209], v[4:7]
	v_mfma_f32_16x16x32_bf16 v[0:3], v[174:177], v[206:209], v[0:3]
	v_mfma_f32_16x16x32_bf16 v[40:43], v[170:173], v[186:189], v[40:43]
	v_mfma_f32_16x16x32_bf16 v[36:39], v[178:181], v[186:189], v[36:39]
	v_mfma_f32_16x16x32_bf16 v[28:31], v[170:173], v[194:197], v[28:31]
	v_mfma_f32_16x16x32_bf16 v[24:27], v[178:181], v[194:197], v[24:27]
	v_mfma_f32_16x16x32_bf16 v[20:23], v[170:173], v[202:205], v[20:23]
	v_mfma_f32_16x16x32_bf16 v[8:11], v[178:181], v[202:205], v[8:11]
	v_mfma_f32_16x16x32_bf16 v[4:7], v[170:173], v[210:213], v[4:7]
	v_mfma_f32_16x16x32_bf16 v[0:3], v[178:181], v[210:213], v[0:3]
	s_setprio 0
	s_barrier
	s_add_i32 s44, 0, 0x18000
	s_add_i32 s45, 0, 0x1c000
	v_add_u32_e32 v140, s44, v166
	v_add_u32_e32 v178, s45, v166
	ds_read_b128 v[128:131], v140
	ds_read_b128 v[132:135], v140 offset:1024
	ds_read_b128 v[136:139], v140 offset:2048
	ds_read_b128 v[140:143], v140 offset:3072
	ds_read_b128 v[160:163], v178
	ds_read_b128 v[170:173], v178 offset:1024
	ds_read_b128 v[174:177], v178 offset:2048
	ds_read_b128 v[178:181], v178 offset:3072
	s_add_u32 s26, s26, 0x40000
	s_addc_u32 s27, s27, 0
	s_mov_b32 m0, s29
	v_lshl_add_u64 v[220:221], s[26:27], 0, v[150:151]
	ds_read_b128 v[182:185], v169 offset:32768
	ds_read_b128 v[186:189], v169 offset:33792
	ds_read_b128 v[190:193], v169 offset:34816
	ds_read_b128 v[194:197], v169 offset:35840
	ds_read_b128 v[198:201], v169 offset:36864
	ds_read_b128 v[202:205], v169 offset:37888
	ds_read_b128 v[206:209], v169 offset:38912
	ds_read_b128 v[210:213], v169 offset:39936
	global_load_lds_dwordx4 v[220:221], off
	v_lshl_add_u64 v[220:221], s[26:27], 0, v[146:147]
	s_mov_b32 m0, s30
	s_nop 0
	global_load_lds_dwordx4 v[220:221], off
	s_waitcnt vmcnt(8)
	s_waitcnt lgkmcnt(0)
	s_barrier
	s_setprio 1
	s_waitcnt lgkmcnt(0)
	v_mfma_f32_16x16x32_bf16 v[124:127], v[128:131], v[182:185], v[124:127]
	v_mfma_f32_16x16x32_bf16 v[120:123], v[136:139], v[182:185], v[120:123]
	v_mfma_f32_16x16x32_bf16 v[116:119], v[128:131], v[190:193], v[116:119]
	v_mfma_f32_16x16x32_bf16 v[112:115], v[136:139], v[190:193], v[112:115]
	v_mfma_f32_16x16x32_bf16 v[108:111], v[128:131], v[198:201], v[108:111]
	v_mfma_f32_16x16x32_bf16 v[96:99], v[136:139], v[198:201], v[96:99]
	v_mfma_f32_16x16x32_bf16 v[80:83], v[128:131], v[206:209], v[80:83]
	v_mfma_f32_16x16x32_bf16 v[76:79], v[136:139], v[206:209], v[76:79]
	v_mfma_f32_16x16x32_bf16 v[124:127], v[132:135], v[186:189], v[124:127]
	v_mfma_f32_16x16x32_bf16 v[120:123], v[140:143], v[186:189], v[120:123]
	v_mfma_f32_16x16x32_bf16 v[116:119], v[132:135], v[194:197], v[116:119]
	v_mfma_f32_16x16x32_bf16 v[112:115], v[140:143], v[194:197], v[112:115]
	v_mfma_f32_16x16x32_bf16 v[108:111], v[132:135], v[202:205], v[108:111]
	v_mfma_f32_16x16x32_bf16 v[96:99], v[140:143], v[202:205], v[96:99]
	v_mfma_f32_16x16x32_bf16 v[80:83], v[132:135], v[210:213], v[80:83]
	v_mfma_f32_16x16x32_bf16 v[76:79], v[140:143], v[210:213], v[76:79]
	s_setprio 0
	s_setprio 1
	v_mfma_f32_16x16x32_bf16 v[104:107], v[160:163], v[182:185], v[104:107]
	v_mfma_f32_16x16x32_bf16 v[100:103], v[174:177], v[182:185], v[100:103]
	v_mfma_f32_16x16x32_bf16 v[92:95], v[160:163], v[190:193], v[92:95]
	v_mfma_f32_16x16x32_bf16 v[88:91], v[174:177], v[190:193], v[88:91]
	v_mfma_f32_16x16x32_bf16 v[84:87], v[160:163], v[198:201], v[84:87]
	v_mfma_f32_16x16x32_bf16 v[72:75], v[174:177], v[198:201], v[72:75]
	v_mfma_f32_16x16x32_bf16 v[68:71], v[160:163], v[206:209], v[68:71]
	v_mfma_f32_16x16x32_bf16 v[64:67], v[174:177], v[206:209], v[64:67]
	v_mfma_f32_16x16x32_bf16 v[104:107], v[170:173], v[186:189], v[104:107]
	v_mfma_f32_16x16x32_bf16 v[100:103], v[178:181], v[186:189], v[100:103]
	v_mfma_f32_16x16x32_bf16 v[92:95], v[170:173], v[194:197], v[92:95]
	v_mfma_f32_16x16x32_bf16 v[88:91], v[178:181], v[194:197], v[88:91]
	v_mfma_f32_16x16x32_bf16 v[84:87], v[170:173], v[202:205], v[84:87]
	v_mfma_f32_16x16x32_bf16 v[72:75], v[178:181], v[202:205], v[72:75]
	v_mfma_f32_16x16x32_bf16 v[68:71], v[170:173], v[210:213], v[68:71]
	v_mfma_f32_16x16x32_bf16 v[64:67], v[178:181], v[210:213], v[64:67]
	s_setprio 0
	s_barrier
	s_add_i32 s26, s44, s33
	v_lshl_add_u64 v[164:165], v[164:165], 0, s[6:7]
	s_mov_b32 m0, s26
	ds_read_b128 v[182:185], v169 offset:49152
	ds_read_b128 v[186:189], v169 offset:50176
	ds_read_b128 v[190:193], v169 offset:51200
	ds_read_b128 v[194:197], v169 offset:52224
	ds_read_b128 v[198:201], v169 offset:53248
	ds_read_b128 v[202:205], v169 offset:54272
	ds_read_b128 v[206:209], v169 offset:55296
	ds_read_b128 v[210:213], v169 offset:56320
	global_load_lds_dwordx4 v[164:165], off
	s_add_i32 m0, s26, 0x2000
	s_add_u32 s24, s24, 0x40080
	v_lshl_add_u64 v[164:165], v[214:215], 0, s[6:7]
	s_addc_u32 s25, s25, 0
	s_add_i32 s26, s45, s33
	global_load_lds_dwordx4 v[164:165], off
	v_lshl_add_u64 v[164:165], s[24:25], 0, v[148:149]
	s_mov_b32 m0, s26
	s_nop 0
	global_load_lds_dwordx4 v[164:165], off
	v_lshl_add_u64 v[164:165], s[24:25], 0, v[144:145]
	s_add_i32 m0, s26, 0x2000
	s_nop 0
	global_load_lds_dwordx4 v[164:165], off
	v_lshl_add_u64 v[164:165], v[216:217], 0, s[6:7]
	s_mov_b32 m0, s34
	s_nop 0
	global_load_lds_dwordx4 v[164:165], off
	v_lshl_add_u64 v[164:165], v[218:219], 0, s[6:7]
	s_mov_b32 m0, s35
	s_nop 0
	global_load_lds_dwordx4 v[164:165], off
	s_waitcnt vmcnt(8)
	s_waitcnt lgkmcnt(0)
	s_barrier
	s_setprio 1
	s_waitcnt lgkmcnt(0)
	v_mfma_f32_16x16x32_bf16 v[60:63], v[128:131], v[182:185], v[60:63]
	v_mfma_f32_16x16x32_bf16 v[56:59], v[136:139], v[182:185], v[56:59]
	v_mfma_f32_16x16x32_bf16 v[52:55], v[128:131], v[190:193], v[52:55]
	v_mfma_f32_16x16x32_bf16 v[48:51], v[136:139], v[190:193], v[48:51]
	v_mfma_f32_16x16x32_bf16 v[44:47], v[128:131], v[198:201], v[44:47]
	v_mfma_f32_16x16x32_bf16 v[32:35], v[136:139], v[198:201], v[32:35]
	v_mfma_f32_16x16x32_bf16 v[16:19], v[128:131], v[206:209], v[16:19]
	v_mfma_f32_16x16x32_bf16 v[12:15], v[136:139], v[206:209], v[12:15]
	v_mfma_f32_16x16x32_bf16 v[60:63], v[132:135], v[186:189], v[60:63]
	v_mfma_f32_16x16x32_bf16 v[56:59], v[140:143], v[186:189], v[56:59]
	v_mfma_f32_16x16x32_bf16 v[52:55], v[132:135], v[194:197], v[52:55]
	v_mfma_f32_16x16x32_bf16 v[48:51], v[140:143], v[194:197], v[48:51]
	v_mfma_f32_16x16x32_bf16 v[44:47], v[132:135], v[202:205], v[44:47]
	v_mfma_f32_16x16x32_bf16 v[32:35], v[140:143], v[202:205], v[32:35]
	v_mfma_f32_16x16x32_bf16 v[16:19], v[132:135], v[210:213], v[16:19]
	v_mfma_f32_16x16x32_bf16 v[12:15], v[140:143], v[210:213], v[12:15]
	s_setprio 0
	s_setprio 1
	v_mfma_f32_16x16x32_bf16 v[40:43], v[160:163], v[182:185], v[40:43]
	v_mfma_f32_16x16x32_bf16 v[36:39], v[174:177], v[182:185], v[36:39]
	v_mfma_f32_16x16x32_bf16 v[28:31], v[160:163], v[190:193], v[28:31]
	v_mfma_f32_16x16x32_bf16 v[24:27], v[174:177], v[190:193], v[24:27]
	v_mfma_f32_16x16x32_bf16 v[20:23], v[160:163], v[198:201], v[20:23]
	v_mfma_f32_16x16x32_bf16 v[8:11], v[174:177], v[198:201], v[8:11]
	v_mfma_f32_16x16x32_bf16 v[4:7], v[160:163], v[206:209], v[4:7]
	v_mfma_f32_16x16x32_bf16 v[0:3], v[174:177], v[206:209], v[0:3]
	v_mfma_f32_16x16x32_bf16 v[40:43], v[170:173], v[186:189], v[40:43]
	v_mfma_f32_16x16x32_bf16 v[36:39], v[178:181], v[186:189], v[36:39]
	v_mfma_f32_16x16x32_bf16 v[28:31], v[170:173], v[194:197], v[28:31]
	v_mfma_f32_16x16x32_bf16 v[24:27], v[178:181], v[194:197], v[24:27]
	v_mfma_f32_16x16x32_bf16 v[20:23], v[170:173], v[202:205], v[20:23]
	v_mfma_f32_16x16x32_bf16 v[8:11], v[178:181], v[202:205], v[8:11]
	v_mfma_f32_16x16x32_bf16 v[4:7], v[170:173], v[210:213], v[4:7]
	v_mfma_f32_16x16x32_bf16 v[0:3], v[178:181], v[210:213], v[0:3]
	s_setprio 0
	s_barrier
	s_add_i32 s43, s43, 2
	s_add_u32 s22, s22, 0x100
	s_addc_u32 s23, s23, 0
	s_add_u32 s41, s41, 0x100
	s_addc_u32 s42, s42, 0
	s_cmp_gt_u32 s43, 13
	s_cbranch_scc0 .LBB0_929
	v_readlane_b32 s22, v255, 4
	v_readlane_b32 s23, v255, 5
	s_and_b64 vcc, exec, s[22:23]
	s_cbranch_vccz .LBB0_932
	s_barrier

.LBB0_1012:
	s_ashr_i32 s19, s18, 31
	s_lshl_b64 s[22:23], s[18:19], 19
	s_add_u32 s22, s88, s22
	s_addc_u32 s23, s89, s23
	s_and_b64 s[24:25], s[6:7], exec
	s_cselect_b32 s9, s23, s1
	s_cselect_b32 s19, s22, s0
	s_ashr_i32 s21, s20, 31
	s_lshl_b64 s[24:25], s[20:21], 19
	v_readlane_b32 s30, v254, 27
	v_readlane_b32 s31, v254, 28
	s_add_u32 s24, s30, s24
	s_addc_u32 s25, s31, s25
	s_and_b64 s[30:31], s[6:7], exec
	s_cselect_b32 s21, s25, s29
	s_cselect_b32 s27, s24, s28
	s_add_u32 s0, s0, 0x40080
	s_addc_u32 s1, s1, 0
	s_add_u32 s34, s28, 0x100
	v_mov_b32_e32 v0, 0
	s_addc_u32 s35, s29, 0
	s_mov_b32 s51, -2
	s_mov_b32 s96, 1
.LBB0_1013:
	ds_read_b128 v[128:131], v220
	ds_read_b128 v[132:135], v220 offset:1024
	ds_read_b128 v[136:139], v220 offset:2048
	ds_read_b128 v[140:143], v220 offset:3072
	ds_read_b128 v[144:147], v221
	ds_read_b128 v[148:151], v221 offset:1024
	ds_read_b128 v[152:155], v221 offset:2048
	ds_read_b128 v[156:159], v221 offset:3072
	s_add_u32 s28, s0, 0xfffc0080
	s_addc_u32 s29, s1, -1
	s_cmp_eq_u32 s51, 12
	s_cselect_b32 s31, s9, s29
	s_cselect_b32 s30, s19, s28
	s_cselect_b32 s29, s21, s35
	s_cselect_b32 s28, s27, s34
	v_lshl_add_u64 v[208:209], s[0:1], 0, v[184:185]
	s_add_i32 m0, s36, 0xc000
	ds_read_b128 v[160:163], v222
	ds_read_b128 v[164:167], v222 offset:1024
	ds_read_b128 v[168:171], v222 offset:2048
	ds_read_b128 v[172:175], v222 offset:3072
	ds_read_b128 v[192:195], v222 offset:4096
	ds_read_b128 v[196:199], v222 offset:5120
	ds_read_b128 v[200:203], v222 offset:6144
	ds_read_b128 v[204:207], v222 offset:7168
	global_load_lds_dwordx4 v[208:209], off
	v_lshl_add_u64 v[208:209], s[0:1], 0, v[186:187]
	s_add_i32 m0, s36, 0xe000
	s_nop 0
	global_load_lds_dwordx4 v[208:209], off
	s_cmp_lg_u32 s96, 0
	s_cbranch_scc0 .Lz_skip_3
	s_mov_b32 s96, 0
	v_mov_b64_e32 v[0:1], 0
	v_mov_b64_e32 v[2:3], 0
	v_mov_b64_e32 v[4:5], 0
	v_mov_b64_e32 v[6:7], 0
	v_mov_b64_e32 v[8:9], 0
	v_mov_b64_e32 v[10:11], 0
	v_mov_b64_e32 v[12:13], 0
	v_mov_b64_e32 v[14:15], 0
	v_mov_b64_e32 v[16:17], 0
	v_mov_b64_e32 v[18:19], 0
	v_mov_b64_e32 v[20:21], 0
	v_mov_b64_e32 v[22:23], 0
	v_mov_b64_e32 v[24:25], 0
	v_mov_b64_e32 v[26:27], 0
	v_mov_b64_e32 v[28:29], 0
	v_mov_b64_e32 v[30:31], 0
	v_mov_b64_e32 v[32:33], 0
	v_mov_b64_e32 v[34:35], 0
	v_mov_b64_e32 v[36:37], 0
	v_mov_b64_e32 v[38:39], 0
	v_mov_b64_e32 v[40:41], 0
	v_mov_b64_e32 v[42:43], 0
	v_mov_b64_e32 v[44:45], 0
	v_mov_b64_e32 v[46:47], 0
	v_mov_b64_e32 v[48:49], 0
	v_mov_b64_e32 v[50:51], 0
	v_mov_b64_e32 v[52:53], 0
	v_mov_b64_e32 v[54:55], 0
	v_mov_b64_e32 v[56:57], 0
	v_mov_b64_e32 v[58:59], 0
	v_mov_b64_e32 v[60:61], 0
	v_mov_b64_e32 v[62:63], 0
	v_mov_b64_e32 v[64:65], 0
	v_mov_b64_e32 v[66:67], 0
	v_mov_b64_e32 v[68:69], 0
	v_mov_b64_e32 v[70:71], 0
	v_mov_b64_e32 v[72:73], 0
	v_mov_b64_e32 v[74:75], 0
	v_mov_b64_e32 v[76:77], 0
	v_mov_b64_e32 v[78:79], 0
	v_mov_b64_e32 v[80:81], 0
	v_mov_b64_e32 v[82:83], 0
	v_mov_b64_e32 v[84:85], 0
	v_mov_b64_e32 v[86:87], 0
	v_mov_b64_e32 v[88:89], 0
	v_mov_b64_e32 v[90:91], 0
	v_mov_b64_e32 v[92:93], 0
	v_mov_b64_e32 v[94:95], 0
	v_mov_b64_e32 v[96:97], 0
	v_mov_b64_e32 v[98:99], 0
	v_mov_b64_e32 v[100:101], 0
	v_mov_b64_e32 v[102:103], 0
	v_mov_b64_e32 v[104:105], 0
	v_mov_b64_e32 v[106:107], 0
	v_mov_b64_e32 v[108:109], 0
	v_mov_b64_e32 v[110:111], 0
	v_mov_b64_e32 v[112:113], 0
	v_mov_b64_e32 v[114:115], 0
	v_mov_b64_e32 v[116:117], 0
	v_mov_b64_e32 v[118:119], 0
	v_mov_b64_e32 v[120:121], 0
	v_mov_b64_e32 v[122:123], 0
	v_mov_b64_e32 v[124:125], 0
	v_mov_b64_e32 v[126:127], 0
.Lz_skip_3:
	s_waitcnt vmcnt(8)
	s_waitcnt lgkmcnt(0)
	s_barrier
	s_setprio 1
	s_waitcnt lgkmcnt(0)
	v_mfma_f32_16x16x32_bf16 v[84:87], v[128:131], v[160:163], v[84:87]
	v_mfma_f32_16x16x32_bf16 v[80:83], v[136:139], v[160:163], v[80:83]
	v_mfma_f32_16x16x32_bf16 v[92:95], v[128:131], v[168:171], v[92:95]
	v_mfma_f32_16x16x32_bf16 v[88:91], v[136:139], v[168:171], v[88:91]
	v_mfma_f32_16x16x32_bf16 v[124:127], v[128:131], v[192:195], v[124:127]
	v_mfma_f32_16x16x32_bf16 v[120:123], v[136:139], v[192:195], v[120:123]
	v_mfma_f32_16x16x32_bf16 v[116:119], v[128:131], v[200:203], v[116:119]
	v_mfma_f32_16x16x32_bf16 v[112:115], v[136:139], v[200:203], v[112:115]
	v_mfma_f32_16x16x32_bf16 v[84:87], v[132:135], v[164:167], v[84:87]
	v_mfma_f32_16x16x32_bf16 v[80:83], v[140:143], v[164:167], v[80:83]
	v_mfma_f32_16x16x32_bf16 v[92:95], v[132:135], v[172:175], v[92:95]
	v_mfma_f32_16x16x32_bf16 v[88:91], v[140:143], v[172:175], v[88:91]
	v_mfma_f32_16x16x32_bf16 v[124:127], v[132:135], v[196:199], v[124:127]
	v_mfma_f32_16x16x32_bf16 v[120:123], v[140:143], v[196:199], v[120:123]
	v_mfma_f32_16x16x32_bf16 v[116:119], v[132:135], v[204:207], v[116:119]
	v_mfma_f32_16x16x32_bf16 v[112:115], v[140:143], v[204:207], v[112:115]
	s_setprio 0
	s_setprio 1
	v_mfma_f32_16x16x32_bf16 v[40:43], v[144:147], v[160:163], v[40:43]
	v_mfma_f32_16x16x32_bf16 v[32:35], v[152:155], v[160:163], v[32:35]
	v_mfma_f32_16x16x32_bf16 v[28:31], v[144:147], v[168:171], v[28:31]
	v_mfma_f32_16x16x32_bf16 v[24:27], v[152:155], v[168:171], v[24:27]
	v_mfma_f32_16x16x32_bf16 v[108:111], v[144:147], v[192:195], v[108:111]
	v_mfma_f32_16x16x32_bf16 v[104:107], v[152:155], v[192:195], v[104:107]
	v_mfma_f32_16x16x32_bf16 v[100:103], v[144:147], v[200:203], v[100:103]
	v_mfma_f32_16x16x32_bf16 v[96:99], v[152:155], v[200:203], v[96:99]
	v_mfma_f32_16x16x32_bf16 v[40:43], v[148:151], v[164:167], v[40:43]
	v_mfma_f32_16x16x32_bf16 v[32:35], v[156:159], v[164:167], v[32:35]
	v_mfma_f32_16x16x32_bf16 v[28:31], v[148:151], v[172:175], v[28:31]
	v_mfma_f32_16x16x32_bf16 v[24:27], v[156:159], v[172:175], v[24:27]
	v_mfma_f32_16x16x32_bf16 v[108:111], v[148:151], v[196:199], v[108:111]
	v_mfma_f32_16x16x32_bf16 v[104:107], v[156:159], v[196:199], v[104:107]
	v_mfma_f32_16x16x32_bf16 v[100:103], v[148:151], v[204:207], v[100:103]
	v_mfma_f32_16x16x32_bf16 v[96:99], v[156:159], v[204:207], v[96:99]
	s_setprio 0
	s_barrier
	s_add_i32 s52, s48, s33
	v_lshl_add_u64 v[208:209], s[28:29], 0, v[178:179]
	s_mov_b32 m0, s52
	ds_read_b128 v[160:163], v222 offset:16384
	ds_read_b128 v[164:167], v222 offset:17408
	ds_read_b128 v[168:171], v222 offset:18432
	ds_read_b128 v[172:175], v222 offset:19456
	ds_read_b128 v[192:195], v222 offset:20480
	ds_read_b128 v[196:199], v222 offset:21504
	ds_read_b128 v[200:203], v222 offset:22528
	ds_read_b128 v[204:207], v222 offset:23552
	global_load_lds_dwordx4 v[208:209], off
	s_add_i32 m0, s52, 0x2000
	s_add_u32 s52, s28, 0x40000
	v_lshl_add_u64 v[210:211], s[28:29], 0, v[182:183]
	s_addc_u32 s53, s29, 0
	s_add_i32 s54, s49, s33
	global_load_lds_dwordx4 v[210:211], off
	v_lshl_add_u64 v[212:213], s[52:53], 0, v[178:179]
	s_mov_b32 m0, s54
	v_lshl_add_u64 v[214:215], s[30:31], 0, v[180:181]
	global_load_lds_dwordx4 v[212:213], off
	v_lshl_add_u64 v[212:213], s[52:53], 0, v[182:183]
	s_add_i32 m0, s54, 0x2000
	s_nop 0
	global_load_lds_dwordx4 v[212:213], off
	v_lshl_add_u64 v[212:213], s[30:31], 0, v[176:177]
	s_mov_b32 m0, s36
	s_nop 0
	global_load_lds_dwordx4 v[212:213], off
	s_mov_b32 m0, s37
	s_nop 0
	global_load_lds_dwordx4 v[214:215], off
	s_waitcnt vmcnt(8)
	s_waitcnt lgkmcnt(0)
	s_barrier
	s_setprio 1
	s_waitcnt lgkmcnt(0)
	v_mfma_f32_16x16x32_bf16 v[76:79], v[128:131], v[160:163], v[76:79]
	v_mfma_f32_16x16x32_bf16 v[72:75], v[136:139], v[160:163], v[72:75]
	v_mfma_f32_16x16x32_bf16 v[68:71], v[128:131], v[168:171], v[68:71]
	v_mfma_f32_16x16x32_bf16 v[64:67], v[136:139], v[168:171], v[64:67]
	v_mfma_f32_16x16x32_bf16 v[44:47], v[128:131], v[192:195], v[44:47]
	v_mfma_f32_16x16x32_bf16 v[36:39], v[136:139], v[192:195], v[36:39]
	v_mfma_f32_16x16x32_bf16 v[12:15], v[128:131], v[200:203], v[12:15]
	v_mfma_f32_16x16x32_bf16 v[8:11], v[136:139], v[200:203], v[8:11]
	v_mfma_f32_16x16x32_bf16 v[76:79], v[132:135], v[164:167], v[76:79]
	v_mfma_f32_16x16x32_bf16 v[72:75], v[140:143], v[164:167], v[72:75]
	v_mfma_f32_16x16x32_bf16 v[68:71], v[132:135], v[172:175], v[68:71]
	v_mfma_f32_16x16x32_bf16 v[64:67], v[140:143], v[172:175], v[64:67]
	v_mfma_f32_16x16x32_bf16 v[44:47], v[132:135], v[196:199], v[44:47]
	v_mfma_f32_16x16x32_bf16 v[36:39], v[140:143], v[196:199], v[36:39]
	v_mfma_f32_16x16x32_bf16 v[12:15], v[132:135], v[204:207], v[12:15]
	v_mfma_f32_16x16x32_bf16 v[8:11], v[140:143], v[204:207], v[8:11]
	s_setprio 0
	s_setprio 1
	v_mfma_f32_16x16x32_bf16 v[60:63], v[144:147], v[160:163], v[60:63]
	v_mfma_f32_16x16x32_bf16 v[56:59], v[152:155], v[160:163], v[56:59]
	v_mfma_f32_16x16x32_bf16 v[52:55], v[144:147], v[168:171], v[52:55]
	v_mfma_f32_16x16x32_bf16 v[48:51], v[152:155], v[168:171], v[48:51]
	v_mfma_f32_16x16x32_bf16 v[20:23], v[144:147], v[192:195], v[20:23]
	v_mfma_f32_16x16x32_bf16 v[16:19], v[152:155], v[192:195], v[16:19]
	v_mfma_f32_16x16x32_bf16 v[4:7], v[144:147], v[200:203], v[4:7]
	v_mfma_f32_16x16x32_bf16 v[0:3], v[152:155], v[200:203], v[0:3]
	v_mfma_f32_16x16x32_bf16 v[60:63], v[148:151], v[164:167], v[60:63]
	v_mfma_f32_16x16x32_bf16 v[56:59], v[156:159], v[164:167], v[56:59]
	v_mfma_f32_16x16x32_bf16 v[52:55], v[148:151], v[172:175], v[52:55]
	v_mfma_f32_16x16x32_bf16 v[48:51], v[156:159], v[172:175], v[48:51]
	v_mfma_f32_16x16x32_bf16 v[20:23], v[148:151], v[196:199], v[20:23]
	v_mfma_f32_16x16x32_bf16 v[16:19], v[156:159], v[196:199], v[16:19]
	v_mfma_f32_16x16x32_bf16 v[4:7], v[148:151], v[204:207], v[4:7]
	v_mfma_f32_16x16x32_bf16 v[0:3], v[156:159], v[204:207], v[0:3]
	s_setprio 0
	s_barrier
	s_add_i32 s52, 0, 0x18000
	s_add_i32 s53, 0, 0x1c000
	v_add_u32_e32 v140, s52, v219
	v_add_u32_e32 v156, s53, v219
	ds_read_b128 v[128:131], v140
	ds_read_b128 v[132:135], v140 offset:1024
	ds_read_b128 v[136:139], v140 offset:2048
	ds_read_b128 v[140:143], v140 offset:3072
	ds_read_b128 v[144:147], v156
	ds_read_b128 v[148:151], v156 offset:1024
	ds_read_b128 v[152:155], v156 offset:2048
	ds_read_b128 v[156:159], v156 offset:3072
	s_add_u32 s30, s30, 0x40000
	s_addc_u32 s31, s31, 0
	s_mov_b32 m0, s38
	v_lshl_add_u64 v[216:217], s[30:31], 0, v[176:177]
	ds_read_b128 v[160:163], v222 offset:32768
	ds_read_b128 v[164:167], v222 offset:33792
	ds_read_b128 v[168:171], v222 offset:34816
	ds_read_b128 v[172:175], v222 offset:35840
	ds_read_b128 v[192:195], v222 offset:36864
	ds_read_b128 v[196:199], v222 offset:37888
	ds_read_b128 v[200:203], v222 offset:38912
	ds_read_b128 v[204:207], v222 offset:39936
	global_load_lds_dwordx4 v[216:217], off
	v_lshl_add_u64 v[216:217], s[30:31], 0, v[180:181]
	s_mov_b32 m0, s39
	s_nop 0
	global_load_lds_dwordx4 v[216:217], off
	s_waitcnt vmcnt(8)
	s_waitcnt lgkmcnt(0)
	s_barrier
	s_setprio 1
	s_waitcnt lgkmcnt(0)
	v_mfma_f32_16x16x32_bf16 v[84:87], v[128:131], v[160:163], v[84:87]
	v_mfma_f32_16x16x32_bf16 v[80:83], v[136:139], v[160:163], v[80:83]
	v_mfma_f32_16x16x32_bf16 v[92:95], v[128:131], v[168:171], v[92:95]
	v_mfma_f32_16x16x32_bf16 v[88:91], v[136:139], v[168:171], v[88:91]
	v_mfma_f32_16x16x32_bf16 v[124:127], v[128:131], v[192:195], v[124:127]
	v_mfma_f32_16x16x32_bf16 v[120:123], v[136:139], v[192:195], v[120:123]
	v_mfma_f32_16x16x32_bf16 v[116:119], v[128:131], v[200:203], v[116:119]
	v_mfma_f32_16x16x32_bf16 v[112:115], v[136:139], v[200:203], v[112:115]
	v_mfma_f32_16x16x32_bf16 v[84:87], v[132:135], v[164:167], v[84:87]
	v_mfma_f32_16x16x32_bf16 v[80:83], v[140:143], v[164:167], v[80:83]
	v_mfma_f32_16x16x32_bf16 v[92:95], v[132:135], v[172:175], v[92:95]
	v_mfma_f32_16x16x32_bf16 v[88:91], v[140:143], v[172:175], v[88:91]
	v_mfma_f32_16x16x32_bf16 v[124:127], v[132:135], v[196:199], v[124:127]
	v_mfma_f32_16x16x32_bf16 v[120:123], v[140:143], v[196:199], v[120:123]
	v_mfma_f32_16x16x32_bf16 v[116:119], v[132:135], v[204:207], v[116:119]
	v_mfma_f32_16x16x32_bf16 v[112:115], v[140:143], v[204:207], v[112:115]
	s_setprio 0
	s_setprio 1
	v_mfma_f32_16x16x32_bf16 v[40:43], v[144:147], v[160:163], v[40:43]
	v_mfma_f32_16x16x32_bf16 v[32:35], v[152:155], v[160:163], v[32:35]
	v_mfma_f32_16x16x32_bf16 v[28:31], v[144:147], v[168:171], v[28:31]
	v_mfma_f32_16x16x32_bf16 v[24:27], v[152:155], v[168:171], v[24:27]
	v_mfma_f32_16x16x32_bf16 v[108:111], v[144:147], v[192:195], v[108:111]
	v_mfma_f32_16x16x32_bf16 v[104:107], v[152:155], v[192:195], v[104:107]
	v_mfma_f32_16x16x32_bf16 v[100:103], v[144:147], v[200:203], v[100:103]
	v_mfma_f32_16x16x32_bf16 v[96:99], v[152:155], v[200:203], v[96:99]
	v_mfma_f32_16x16x32_bf16 v[40:43], v[148:151], v[164:167], v[40:43]
	v_mfma_f32_16x16x32_bf16 v[32:35], v[156:159], v[164:167], v[32:35]
	v_mfma_f32_16x16x32_bf16 v[28:31], v[148:151], v[172:175], v[28:31]
	v_mfma_f32_16x16x32_bf16 v[24:27], v[156:159], v[172:175], v[24:27]
	v_mfma_f32_16x16x32_bf16 v[108:111], v[148:151], v[196:199], v[108:111]
	v_mfma_f32_16x16x32_bf16 v[104:107], v[156:159], v[196:199], v[104:107]
	v_mfma_f32_16x16x32_bf16 v[100:103], v[148:151], v[204:207], v[100:103]
	v_mfma_f32_16x16x32_bf16 v[96:99], v[156:159], v[204:207], v[96:99]
	s_setprio 0
	s_barrier
	s_add_i32 s30, s52, s33
	v_lshl_add_u64 v[208:209], v[208:209], 0, s[14:15]
	s_mov_b32 m0, s30
	ds_read_b128 v[160:163], v222 offset:49152
	ds_read_b128 v[164:167], v222 offset:50176
	ds_read_b128 v[168:171], v222 offset:51200
	ds_read_b128 v[172:175], v222 offset:52224
	ds_read_b128 v[192:195], v222 offset:53248
	ds_read_b128 v[196:199], v222 offset:54272
	ds_read_b128 v[200:203], v222 offset:55296
	ds_read_b128 v[204:207], v222 offset:56320
	global_load_lds_dwordx4 v[208:209], off
	s_add_i32 m0, s30, 0x2000
	s_add_u32 s28, s28, 0x40080
	v_lshl_add_u64 v[208:209], v[210:211], 0, s[14:15]
	s_addc_u32 s29, s29, 0
	s_add_i32 s30, s53, s33
	global_load_lds_dwordx4 v[208:209], off
	v_lshl_add_u64 v[208:209], s[28:29], 0, v[178:179]
	s_mov_b32 m0, s30
	s_nop 0
	global_load_lds_dwordx4 v[208:209], off
	v_lshl_add_u64 v[208:209], s[28:29], 0, v[182:183]
	s_add_i32 m0, s30, 0x2000
	s_nop 0
	global_load_lds_dwordx4 v[208:209], off
	v_lshl_add_u64 v[208:209], v[212:213], 0, s[14:15]
	s_mov_b32 m0, s42
	s_nop 0
	global_load_lds_dwordx4 v[208:209], off
	v_lshl_add_u64 v[208:209], v[214:215], 0, s[14:15]
	s_mov_b32 m0, s43
	s_nop 0
	global_load_lds_dwordx4 v[208:209], off
	s_waitcnt vmcnt(8)
	s_waitcnt lgkmcnt(0)
	s_barrier
	s_setprio 1
	s_waitcnt lgkmcnt(0)
	v_mfma_f32_16x16x32_bf16 v[76:79], v[128:131], v[160:163], v[76:79]
	v_mfma_f32_16x16x32_bf16 v[72:75], v[136:139], v[160:163], v[72:75]
	v_mfma_f32_16x16x32_bf16 v[68:71], v[128:131], v[168:171], v[68:71]
	v_mfma_f32_16x16x32_bf16 v[64:67], v[136:139], v[168:171], v[64:67]
	v_mfma_f32_16x16x32_bf16 v[44:47], v[128:131], v[192:195], v[44:47]
	v_mfma_f32_16x16x32_bf16 v[36:39], v[136:139], v[192:195], v[36:39]
	v_mfma_f32_16x16x32_bf16 v[12:15], v[128:131], v[200:203], v[12:15]
	v_mfma_f32_16x16x32_bf16 v[8:11], v[136:139], v[200:203], v[8:11]
	v_mfma_f32_16x16x32_bf16 v[76:79], v[132:135], v[164:167], v[76:79]
	v_mfma_f32_16x16x32_bf16 v[72:75], v[140:143], v[164:167], v[72:75]
	v_mfma_f32_16x16x32_bf16 v[68:71], v[132:135], v[172:175], v[68:71]
	v_mfma_f32_16x16x32_bf16 v[64:67], v[140:143], v[172:175], v[64:67]
	v_mfma_f32_16x16x32_bf16 v[44:47], v[132:135], v[196:199], v[44:47]
	v_mfma_f32_16x16x32_bf16 v[36:39], v[140:143], v[196:199], v[36:39]
	v_mfma_f32_16x16x32_bf16 v[12:15], v[132:135], v[204:207], v[12:15]
	v_mfma_f32_16x16x32_bf16 v[8:11], v[140:143], v[204:207], v[8:11]
	s_setprio 0
	s_setprio 1
	v_mfma_f32_16x16x32_bf16 v[60:63], v[144:147], v[160:163], v[60:63]
	v_mfma_f32_16x16x32_bf16 v[56:59], v[152:155], v[160:163], v[56:59]
	v_mfma_f32_16x16x32_bf16 v[52:55], v[144:147], v[168:171], v[52:55]
	v_mfma_f32_16x16x32_bf16 v[48:51], v[152:155], v[168:171], v[48:51]
	v_mfma_f32_16x16x32_bf16 v[20:23], v[144:147], v[192:195], v[20:23]
	v_mfma_f32_16x16x32_bf16 v[16:19], v[152:155], v[192:195], v[16:19]
	v_mfma_f32_16x16x32_bf16 v[4:7], v[144:147], v[200:203], v[4:7]
	v_mfma_f32_16x16x32_bf16 v[0:3], v[152:155], v[200:203], v[0:3]
	v_mfma_f32_16x16x32_bf16 v[60:63], v[148:151], v[164:167], v[60:63]
	v_mfma_f32_16x16x32_bf16 v[56:59], v[156:159], v[164:167], v[56:59]
	v_mfma_f32_16x16x32_bf16 v[52:55], v[148:151], v[172:175], v[52:55]
	v_mfma_f32_16x16x32_bf16 v[48:51], v[156:159], v[172:175], v[48:51]
	v_mfma_f32_16x16x32_bf16 v[20:23], v[148:151], v[196:199], v[20:23]
	v_mfma_f32_16x16x32_bf16 v[16:19], v[156:159], v[196:199], v[16:19]
	v_mfma_f32_16x16x32_bf16 v[4:7], v[148:151], v[204:207], v[4:7]
	v_mfma_f32_16x16x32_bf16 v[0:3], v[156:159], v[204:207], v[0:3]
	s_setprio 0
	s_barrier
	s_add_i32 s51, s51, 2
	s_add_u32 s0, s0, 0x100
	s_addc_u32 s1, s1, 0
	s_add_u32 s34, s34, 0x100
	s_addc_u32 s35, s35, 0
	s_cmp_gt_u32 s51, 13
	s_cbranch_scc0 .LBB0_1013
	v_readlane_b32 s0, v255, 4
	v_readlane_b32 s1, v255, 5
	s_and_b64 vcc, exec, s[0:1]
	s_cbranch_vccz .LBB0_1016
	s_barrier

.LBB0_1101:
	s_ashr_i32 s11, s10, 31
	s_lshl_b64 s[12:13], s[10:11], 19
	v_readlane_b32 s14, v255, 47
	v_readlane_b32 s15, v255, 48
	s_add_u32 s12, s14, s12
	s_addc_u32 s13, s15, s13
	s_and_b64 s[14:15], s[6:7], exec
	s_cselect_b32 s11, s13, s19
	s_cselect_b32 s38, s12, s18
	s_ashr_i32 s9, s8, 31
	s_lshl_b64 s[14:15], s[8:9], 19
	v_readlane_b32 s22, v254, 29
	v_readlane_b32 s23, v254, 30
	s_add_u32 s14, s22, s14
	s_addc_u32 s15, s23, s15
	s_and_b64 s[22:23], s[6:7], exec
	s_cselect_b32 s9, s15, s21
	s_cselect_b32 s39, s14, s20
	s_add_u32 s18, s18, 0x40080
	s_addc_u32 s19, s19, 0
	s_add_u32 s40, s20, 0x100
	v_mov_b32_e32 v0, 0
	s_addc_u32 s41, s21, 0
	s_mov_b32 s42, -2
	s_mov_b32 s96, 1
.LBB0_1102:
	ds_read_b128 v[148:151], v145
	ds_read_b128 v[152:155], v145 offset:1024
	ds_read_b128 v[156:159], v145 offset:2048
	ds_read_b128 v[160:163], v145 offset:3072
	ds_read_b128 v[164:167], v146
	ds_read_b128 v[168:171], v146 offset:1024
	ds_read_b128 v[172:175], v146 offset:2048
	ds_read_b128 v[176:179], v146 offset:3072
	s_add_u32 s20, s18, 0xfffc0080
	s_addc_u32 s21, s19, -1
	s_cmp_eq_u32 s42, 12
	s_cselect_b32 s23, s11, s21
	s_cselect_b32 s22, s38, s20
	s_cselect_b32 s21, s9, s41
	s_cselect_b32 s20, s39, s40
	v_lshl_add_u64 v[212:213], s[18:19], 0, v[136:137]
	s_add_i32 m0, s17, 0xc000
	ds_read_b128 v[180:183], v147
	ds_read_b128 v[184:187], v147 offset:1024
	ds_read_b128 v[188:191], v147 offset:2048
	ds_read_b128 v[192:195], v147 offset:3072
	ds_read_b128 v[196:199], v147 offset:4096
	ds_read_b128 v[200:203], v147 offset:5120
	ds_read_b128 v[204:207], v147 offset:6144
	ds_read_b128 v[208:211], v147 offset:7168
	global_load_lds_dwordx4 v[212:213], off
	v_lshl_add_u64 v[212:213], s[18:19], 0, v[138:139]
	s_add_i32 m0, s17, 0xe000
	s_nop 0
	global_load_lds_dwordx4 v[212:213], off
	s_cmp_lg_u32 s96, 0
	s_cbranch_scc0 .Lz_skip_2
	s_mov_b32 s96, 0
	v_mov_b64_e32 v[0:1], 0
	v_mov_b64_e32 v[2:3], 0
	v_mov_b64_e32 v[4:5], 0
	v_mov_b64_e32 v[6:7], 0
	v_mov_b64_e32 v[8:9], 0
	v_mov_b64_e32 v[10:11], 0
	v_mov_b64_e32 v[12:13], 0
	v_mov_b64_e32 v[14:15], 0
	v_mov_b64_e32 v[16:17], 0
	v_mov_b64_e32 v[18:19], 0
	v_mov_b64_e32 v[20:21], 0
	v_mov_b64_e32 v[22:23], 0
	v_mov_b64_e32 v[24:25], 0
	v_mov_b64_e32 v[26:27], 0
	v_mov_b64_e32 v[28:29], 0
	v_mov_b64_e32 v[30:31], 0
	v_mov_b64_e32 v[32:33], 0
	v_mov_b64_e32 v[34:35], 0
	v_mov_b64_e32 v[36:37], 0
	v_mov_b64_e32 v[38:39], 0
	v_mov_b64_e32 v[40:41], 0
	v_mov_b64_e32 v[42:43], 0
	v_mov_b64_e32 v[44:45], 0
	v_mov_b64_e32 v[46:47], 0
	v_mov_b64_e32 v[48:49], 0
	v_mov_b64_e32 v[50:51], 0
	v_mov_b64_e32 v[52:53], 0
	v_mov_b64_e32 v[54:55], 0
	v_mov_b64_e32 v[56:57], 0
	v_mov_b64_e32 v[58:59], 0
	v_mov_b64_e32 v[60:61], 0
	v_mov_b64_e32 v[62:63], 0
	v_mov_b64_e32 v[64:65], 0
	v_mov_b64_e32 v[66:67], 0
	v_mov_b64_e32 v[68:69], 0
	v_mov_b64_e32 v[70:71], 0
	v_mov_b64_e32 v[72:73], 0
	v_mov_b64_e32 v[74:75], 0
	v_mov_b64_e32 v[76:77], 0
	v_mov_b64_e32 v[78:79], 0
	v_mov_b64_e32 v[80:81], 0
	v_mov_b64_e32 v[82:83], 0
	v_mov_b64_e32 v[84:85], 0
	v_mov_b64_e32 v[86:87], 0
	v_mov_b64_e32 v[88:89], 0
	v_mov_b64_e32 v[90:91], 0
	v_mov_b64_e32 v[92:93], 0
	v_mov_b64_e32 v[94:95], 0
	v_mov_b64_e32 v[96:97], 0
	v_mov_b64_e32 v[98:99], 0
	v_mov_b64_e32 v[100:101], 0
	v_mov_b64_e32 v[102:103], 0
	v_mov_b64_e32 v[104:105], 0
	v_mov_b64_e32 v[106:107], 0
	v_mov_b64_e32 v[108:109], 0
	v_mov_b64_e32 v[110:111], 0
	v_mov_b64_e32 v[112:113], 0
	v_mov_b64_e32 v[114:115], 0
	v_mov_b64_e32 v[116:117], 0
	v_mov_b64_e32 v[118:119], 0
	v_mov_b64_e32 v[120:121], 0
	v_mov_b64_e32 v[122:123], 0
	v_mov_b64_e32 v[124:125], 0
	v_mov_b64_e32 v[126:127], 0
.Lz_skip_2:
	s_waitcnt vmcnt(8)
	s_waitcnt lgkmcnt(0)
	s_barrier
	s_setprio 1
	s_waitcnt lgkmcnt(0)
	v_mfma_f32_16x16x32_bf16 v[124:127], v[148:151], v[180:183], v[124:127]
	v_mfma_f32_16x16x32_bf16 v[120:123], v[156:159], v[180:183], v[120:123]
	v_mfma_f32_16x16x32_bf16 v[116:119], v[148:151], v[188:191], v[116:119]
	v_mfma_f32_16x16x32_bf16 v[112:115], v[156:159], v[188:191], v[112:115]
	v_mfma_f32_16x16x32_bf16 v[92:95], v[148:151], v[196:199], v[92:95]
	v_mfma_f32_16x16x32_bf16 v[88:91], v[156:159], v[196:199], v[88:91]
	v_mfma_f32_16x16x32_bf16 v[84:87], v[148:151], v[204:207], v[84:87]
	v_mfma_f32_16x16x32_bf16 v[80:83], v[156:159], v[204:207], v[80:83]
	v_mfma_f32_16x16x32_bf16 v[124:127], v[152:155], v[184:187], v[124:127]
	v_mfma_f32_16x16x32_bf16 v[120:123], v[160:163], v[184:187], v[120:123]
	v_mfma_f32_16x16x32_bf16 v[116:119], v[152:155], v[192:195], v[116:119]
	v_mfma_f32_16x16x32_bf16 v[112:115], v[160:163], v[192:195], v[112:115]
	v_mfma_f32_16x16x32_bf16 v[92:95], v[152:155], v[200:203], v[92:95]
	v_mfma_f32_16x16x32_bf16 v[88:91], v[160:163], v[200:203], v[88:91]
	v_mfma_f32_16x16x32_bf16 v[84:87], v[152:155], v[208:211], v[84:87]
	v_mfma_f32_16x16x32_bf16 v[80:83], v[160:163], v[208:211], v[80:83]
	s_setprio 0
	s_setprio 1
	v_mfma_f32_16x16x32_bf16 v[108:111], v[164:167], v[180:183], v[108:111]
	v_mfma_f32_16x16x32_bf16 v[104:107], v[172:175], v[180:183], v[104:107]
	v_mfma_f32_16x16x32_bf16 v[100:103], v[164:167], v[188:191], v[100:103]
	v_mfma_f32_16x16x32_bf16 v[96:99], v[172:175], v[188:191], v[96:99]
	v_mfma_f32_16x16x32_bf16 v[76:79], v[164:167], v[196:199], v[76:79]
	v_mfma_f32_16x16x32_bf16 v[72:75], v[172:175], v[196:199], v[72:75]
	v_mfma_f32_16x16x32_bf16 v[68:71], v[164:167], v[204:207], v[68:71]
	v_mfma_f32_16x16x32_bf16 v[64:67], v[172:175], v[204:207], v[64:67]
	v_mfma_f32_16x16x32_bf16 v[108:111], v[168:171], v[184:187], v[108:111]
	v_mfma_f32_16x16x32_bf16 v[104:107], v[176:179], v[184:187], v[104:107]
	v_mfma_f32_16x16x32_bf16 v[100:103], v[168:171], v[192:195], v[100:103]
	v_mfma_f32_16x16x32_bf16 v[96:99], v[176:179], v[192:195], v[96:99]
	v_mfma_f32_16x16x32_bf16 v[76:79], v[168:171], v[200:203], v[76:79]
	v_mfma_f32_16x16x32_bf16 v[72:75], v[176:179], v[200:203], v[72:75]
	v_mfma_f32_16x16x32_bf16 v[68:71], v[168:171], v[208:211], v[68:71]
	v_mfma_f32_16x16x32_bf16 v[64:67], v[176:179], v[208:211], v[64:67]
	s_setprio 0
	s_barrier
	s_add_i32 s43, s34, s33
	v_lshl_add_u64 v[212:213], s[20:21], 0, v[132:133]
	s_mov_b32 m0, s43
	ds_read_b128 v[180:183], v147 offset:16384
	ds_read_b128 v[184:187], v147 offset:17408
	ds_read_b128 v[188:191], v147 offset:18432
	ds_read_b128 v[192:195], v147 offset:19456
	ds_read_b128 v[196:199], v147 offset:20480
	ds_read_b128 v[200:203], v147 offset:21504
	ds_read_b128 v[204:207], v147 offset:22528
	ds_read_b128 v[208:211], v147 offset:23552
	global_load_lds_dwordx4 v[212:213], off
	s_add_i32 m0, s43, 0x2000
	s_add_u32 s44, s20, 0x40000
	v_lshl_add_u64 v[214:215], s[20:21], 0, v[128:129]
	s_addc_u32 s45, s21, 0
	s_add_i32 s43, s35, s33
	global_load_lds_dwordx4 v[214:215], off
	v_lshl_add_u64 v[216:217], s[44:45], 0, v[132:133]
	s_mov_b32 m0, s43
	v_lshl_add_u64 v[218:219], s[22:23], 0, v[130:131]
	global_load_lds_dwordx4 v[216:217], off
	v_lshl_add_u64 v[216:217], s[44:45], 0, v[128:129]
	s_add_i32 m0, s43, 0x2000
	s_nop 0
	global_load_lds_dwordx4 v[216:217], off
	v_lshl_add_u64 v[216:217], s[22:23], 0, v[134:135]
	s_mov_b32 m0, s17
	s_nop 0
	global_load_lds_dwordx4 v[216:217], off
	s_mov_b32 m0, s25
	s_nop 0
	global_load_lds_dwordx4 v[218:219], off
	s_waitcnt vmcnt(8)
	s_waitcnt lgkmcnt(0)
	s_barrier
	s_setprio 1
	s_waitcnt lgkmcnt(0)
	v_mfma_f32_16x16x32_bf16 v[60:63], v[148:151], v[180:183], v[60:63]
	v_mfma_f32_16x16x32_bf16 v[56:59], v[156:159], v[180:183], v[56:59]
	v_mfma_f32_16x16x32_bf16 v[52:55], v[148:151], v[188:191], v[52:55]
	v_mfma_f32_16x16x32_bf16 v[48:51], v[156:159], v[188:191], v[48:51]
	v_mfma_f32_16x16x32_bf16 v[28:31], v[148:151], v[196:199], v[28:31]
	v_mfma_f32_16x16x32_bf16 v[24:27], v[156:159], v[196:199], v[24:27]
	v_mfma_f32_16x16x32_bf16 v[20:23], v[148:151], v[204:207], v[20:23]
	v_mfma_f32_16x16x32_bf16 v[16:19], v[156:159], v[204:207], v[16:19]
	v_mfma_f32_16x16x32_bf16 v[60:63], v[152:155], v[184:187], v[60:63]
	v_mfma_f32_16x16x32_bf16 v[56:59], v[160:163], v[184:187], v[56:59]
	v_mfma_f32_16x16x32_bf16 v[52:55], v[152:155], v[192:195], v[52:55]
	v_mfma_f32_16x16x32_bf16 v[48:51], v[160:163], v[192:195], v[48:51]
	v_mfma_f32_16x16x32_bf16 v[28:31], v[152:155], v[200:203], v[28:31]
	v_mfma_f32_16x16x32_bf16 v[24:27], v[160:163], v[200:203], v[24:27]
	v_mfma_f32_16x16x32_bf16 v[20:23], v[152:155], v[208:211], v[20:23]
	v_mfma_f32_16x16x32_bf16 v[16:19], v[160:163], v[208:211], v[16:19]
	s_setprio 0
	s_setprio 1
	v_mfma_f32_16x16x32_bf16 v[44:47], v[164:167], v[180:183], v[44:47]
	v_mfma_f32_16x16x32_bf16 v[40:43], v[172:175], v[180:183], v[40:43]
	v_mfma_f32_16x16x32_bf16 v[36:39], v[164:167], v[188:191], v[36:39]
	v_mfma_f32_16x16x32_bf16 v[32:35], v[172:175], v[188:191], v[32:35]
	v_mfma_f32_16x16x32_bf16 v[12:15], v[164:167], v[196:199], v[12:15]
	v_mfma_f32_16x16x32_bf16 v[8:11], v[172:175], v[196:199], v[8:11]
	v_mfma_f32_16x16x32_bf16 v[4:7], v[164:167], v[204:207], v[4:7]
	v_mfma_f32_16x16x32_bf16 v[0:3], v[172:175], v[204:207], v[0:3]
	v_mfma_f32_16x16x32_bf16 v[44:47], v[168:171], v[184:187], v[44:47]
	v_mfma_f32_16x16x32_bf16 v[40:43], v[176:179], v[184:187], v[40:43]
	v_mfma_f32_16x16x32_bf16 v[36:39], v[168:171], v[192:195], v[36:39]
	v_mfma_f32_16x16x32_bf16 v[32:35], v[176:179], v[192:195], v[32:35]
	v_mfma_f32_16x16x32_bf16 v[12:15], v[168:171], v[200:203], v[12:15]
	v_mfma_f32_16x16x32_bf16 v[8:11], v[176:179], v[200:203], v[8:11]
	v_mfma_f32_16x16x32_bf16 v[4:7], v[168:171], v[208:211], v[4:7]
	v_mfma_f32_16x16x32_bf16 v[0:3], v[176:179], v[208:211], v[0:3]
	s_setprio 0
	s_barrier
	s_add_i32 s43, 0, 0x18000
	s_add_i32 s44, 0, 0x1c000
	v_add_u32_e32 v160, s43, v144
	v_add_u32_e32 v176, s44, v144
	ds_read_b128 v[148:151], v160
	ds_read_b128 v[152:155], v160 offset:1024
	ds_read_b128 v[156:159], v160 offset:2048
	ds_read_b128 v[160:163], v160 offset:3072
	ds_read_b128 v[164:167], v176
	ds_read_b128 v[168:171], v176 offset:1024
	ds_read_b128 v[172:175], v176 offset:2048
	ds_read_b128 v[176:179], v176 offset:3072
	s_add_u32 s22, s22, 0x40000
	s_addc_u32 s23, s23, 0
	s_mov_b32 m0, s26
	v_lshl_add_u64 v[220:221], s[22:23], 0, v[134:135]
	ds_read_b128 v[180:183], v147 offset:32768
	ds_read_b128 v[184:187], v147 offset:33792
	ds_read_b128 v[188:191], v147 offset:34816
	ds_read_b128 v[192:195], v147 offset:35840
	ds_read_b128 v[196:199], v147 offset:36864
	ds_read_b128 v[200:203], v147 offset:37888
	ds_read_b128 v[204:207], v147 offset:38912
	ds_read_b128 v[208:211], v147 offset:39936
	global_load_lds_dwordx4 v[220:221], off
	v_lshl_add_u64 v[220:221], s[22:23], 0, v[130:131]
	s_mov_b32 m0, s27
	s_nop 0
	global_load_lds_dwordx4 v[220:221], off
	s_waitcnt vmcnt(8)
	s_waitcnt lgkmcnt(0)
	s_barrier
	s_setprio 1
	s_waitcnt lgkmcnt(0)
	v_mfma_f32_16x16x32_bf16 v[124:127], v[148:151], v[180:183], v[124:127]
	v_mfma_f32_16x16x32_bf16 v[120:123], v[156:159], v[180:183], v[120:123]
	v_mfma_f32_16x16x32_bf16 v[116:119], v[148:151], v[188:191], v[116:119]
	v_mfma_f32_16x16x32_bf16 v[112:115], v[156:159], v[188:191], v[112:115]
	v_mfma_f32_16x16x32_bf16 v[92:95], v[148:151], v[196:199], v[92:95]
	v_mfma_f32_16x16x32_bf16 v[88:91], v[156:159], v[196:199], v[88:91]
	v_mfma_f32_16x16x32_bf16 v[84:87], v[148:151], v[204:207], v[84:87]
	v_mfma_f32_16x16x32_bf16 v[80:83], v[156:159], v[204:207], v[80:83]
	v_mfma_f32_16x16x32_bf16 v[124:127], v[152:155], v[184:187], v[124:127]
	v_mfma_f32_16x16x32_bf16 v[120:123], v[160:163], v[184:187], v[120:123]
	v_mfma_f32_16x16x32_bf16 v[116:119], v[152:155], v[192:195], v[116:119]
	v_mfma_f32_16x16x32_bf16 v[112:115], v[160:163], v[192:195], v[112:115]
	v_mfma_f32_16x16x32_bf16 v[92:95], v[152:155], v[200:203], v[92:95]
	v_mfma_f32_16x16x32_bf16 v[88:91], v[160:163], v[200:203], v[88:91]
	v_mfma_f32_16x16x32_bf16 v[84:87], v[152:155], v[208:211], v[84:87]
	v_mfma_f32_16x16x32_bf16 v[80:83], v[160:163], v[208:211], v[80:83]
	s_setprio 0
	s_setprio 1
	v_mfma_f32_16x16x32_bf16 v[108:111], v[164:167], v[180:183], v[108:111]
	v_mfma_f32_16x16x32_bf16 v[104:107], v[172:175], v[180:183], v[104:107]
	v_mfma_f32_16x16x32_bf16 v[100:103], v[164:167], v[188:191], v[100:103]
	v_mfma_f32_16x16x32_bf16 v[96:99], v[172:175], v[188:191], v[96:99]
	v_mfma_f32_16x16x32_bf16 v[76:79], v[164:167], v[196:199], v[76:79]
	v_mfma_f32_16x16x32_bf16 v[72:75], v[172:175], v[196:199], v[72:75]
	v_mfma_f32_16x16x32_bf16 v[68:71], v[164:167], v[204:207], v[68:71]
	v_mfma_f32_16x16x32_bf16 v[64:67], v[172:175], v[204:207], v[64:67]
	v_mfma_f32_16x16x32_bf16 v[108:111], v[168:171], v[184:187], v[108:111]
	v_mfma_f32_16x16x32_bf16 v[104:107], v[176:179], v[184:187], v[104:107]
	v_mfma_f32_16x16x32_bf16 v[100:103], v[168:171], v[192:195], v[100:103]
	v_mfma_f32_16x16x32_bf16 v[96:99], v[176:179], v[192:195], v[96:99]
	v_mfma_f32_16x16x32_bf16 v[76:79], v[168:171], v[200:203], v[76:79]
	v_mfma_f32_16x16x32_bf16 v[72:75], v[176:179], v[200:203], v[72:75]
	v_mfma_f32_16x16x32_bf16 v[68:71], v[168:171], v[208:211], v[68:71]
	v_mfma_f32_16x16x32_bf16 v[64:67], v[176:179], v[208:211], v[64:67]
	s_setprio 0
	s_barrier
	s_add_i32 s22, s43, s33
	v_lshl_add_u64 v[212:213], v[212:213], 0, s[0:1]
	s_mov_b32 m0, s22
	ds_read_b128 v[180:183], v147 offset:49152
	ds_read_b128 v[184:187], v147 offset:50176
	ds_read_b128 v[188:191], v147 offset:51200
	ds_read_b128 v[192:195], v147 offset:52224
	ds_read_b128 v[196:199], v147 offset:53248
	ds_read_b128 v[200:203], v147 offset:54272
	ds_read_b128 v[204:207], v147 offset:55296
	ds_read_b128 v[208:211], v147 offset:56320
	global_load_lds_dwordx4 v[212:213], off
	s_add_i32 m0, s22, 0x2000
	s_add_u32 s20, s20, 0x40080
	v_lshl_add_u64 v[212:213], v[214:215], 0, s[0:1]
	s_addc_u32 s21, s21, 0
	s_add_i32 s22, s44, s33
	global_load_lds_dwordx4 v[212:213], off
	v_lshl_add_u64 v[212:213], s[20:21], 0, v[132:133]
	s_mov_b32 m0, s22
	s_nop 0
	global_load_lds_dwordx4 v[212:213], off
	v_lshl_add_u64 v[212:213], s[20:21], 0, v[128:129]
	s_add_i32 m0, s22, 0x2000
	s_nop 0
	global_load_lds_dwordx4 v[212:213], off
	v_lshl_add_u64 v[212:213], v[216:217], 0, s[0:1]
	s_mov_b32 m0, s30
	s_nop 0
	global_load_lds_dwordx4 v[212:213], off
	v_lshl_add_u64 v[212:213], v[218:219], 0, s[0:1]
	s_mov_b32 m0, s31
	s_nop 0
	global_load_lds_dwordx4 v[212:213], off
	s_waitcnt vmcnt(8)
	s_waitcnt lgkmcnt(0)
	s_barrier
	s_setprio 1
	s_waitcnt lgkmcnt(0)
	v_mfma_f32_16x16x32_bf16 v[60:63], v[148:151], v[180:183], v[60:63]
	v_mfma_f32_16x16x32_bf16 v[56:59], v[156:159], v[180:183], v[56:59]
	v_mfma_f32_16x16x32_bf16 v[52:55], v[148:151], v[188:191], v[52:55]
	v_mfma_f32_16x16x32_bf16 v[48:51], v[156:159], v[188:191], v[48:51]
	v_mfma_f32_16x16x32_bf16 v[28:31], v[148:151], v[196:199], v[28:31]
	v_mfma_f32_16x16x32_bf16 v[24:27], v[156:159], v[196:199], v[24:27]
	v_mfma_f32_16x16x32_bf16 v[20:23], v[148:151], v[204:207], v[20:23]
	v_mfma_f32_16x16x32_bf16 v[16:19], v[156:159], v[204:207], v[16:19]
	v_mfma_f32_16x16x32_bf16 v[60:63], v[152:155], v[184:187], v[60:63]
	v_mfma_f32_16x16x32_bf16 v[56:59], v[160:163], v[184:187], v[56:59]
	v_mfma_f32_16x16x32_bf16 v[52:55], v[152:155], v[192:195], v[52:55]
	v_mfma_f32_16x16x32_bf16 v[48:51], v[160:163], v[192:195], v[48:51]
	v_mfma_f32_16x16x32_bf16 v[28:31], v[152:155], v[200:203], v[28:31]
	v_mfma_f32_16x16x32_bf16 v[24:27], v[160:163], v[200:203], v[24:27]
	v_mfma_f32_16x16x32_bf16 v[20:23], v[152:155], v[208:211], v[20:23]
	v_mfma_f32_16x16x32_bf16 v[16:19], v[160:163], v[208:211], v[16:19]
	s_setprio 0
	s_setprio 1
	v_mfma_f32_16x16x32_bf16 v[44:47], v[164:167], v[180:183], v[44:47]
	v_mfma_f32_16x16x32_bf16 v[40:43], v[172:175], v[180:183], v[40:43]
	v_mfma_f32_16x16x32_bf16 v[36:39], v[164:167], v[188:191], v[36:39]
	v_mfma_f32_16x16x32_bf16 v[32:35], v[172:175], v[188:191], v[32:35]
	v_mfma_f32_16x16x32_bf16 v[12:15], v[164:167], v[196:199], v[12:15]
	v_mfma_f32_16x16x32_bf16 v[8:11], v[172:175], v[196:199], v[8:11]
	v_mfma_f32_16x16x32_bf16 v[4:7], v[164:167], v[204:207], v[4:7]
	v_mfma_f32_16x16x32_bf16 v[0:3], v[172:175], v[204:207], v[0:3]
	v_mfma_f32_16x16x32_bf16 v[44:47], v[168:171], v[184:187], v[44:47]
	v_mfma_f32_16x16x32_bf16 v[40:43], v[176:179], v[184:187], v[40:43]
	v_mfma_f32_16x16x32_bf16 v[36:39], v[168:171], v[192:195], v[36:39]
	v_mfma_f32_16x16x32_bf16 v[32:35], v[176:179], v[192:195], v[32:35]
	v_mfma_f32_16x16x32_bf16 v[12:15], v[168:171], v[200:203], v[12:15]
	v_mfma_f32_16x16x32_bf16 v[8:11], v[176:179], v[200:203], v[8:11]
	v_mfma_f32_16x16x32_bf16 v[4:7], v[168:171], v[208:211], v[4:7]
	v_mfma_f32_16x16x32_bf16 v[0:3], v[176:179], v[208:211], v[0:3]
	s_setprio 0
	s_barrier
	s_add_i32 s42, s42, 2
	s_add_u32 s18, s18, 0x100
	s_addc_u32 s19, s19, 0
	s_add_u32 s40, s40, 0x100
	s_addc_u32 s41, s41, 0
	s_cmp_gt_u32 s42, 13
	s_cbranch_scc0 .LBB0_1102
	v_readlane_b32 s18, v255, 4
	v_readlane_b32 s19, v255, 5
	s_and_b64 vcc, exec, s[18:19]
	s_cbranch_vccz .LBB0_1105
	s_barrier

.LBB0_1183:
	s_add_u32 s41, s20, 0x100
	v_mov_b32_e32 v0, 0
	s_addc_u32 s42, s21, 0
	s_mov_b32 s43, -2
	s_mov_b32 s96, 1
.LBB0_1184:
	ds_read_b128 v[128:131], v167
	ds_read_b128 v[132:135], v167 offset:1024
	ds_read_b128 v[136:139], v167 offset:2048
	ds_read_b128 v[140:143], v167 offset:3072
	ds_read_b128 v[160:163], v168
	ds_read_b128 v[170:173], v168 offset:1024
	ds_read_b128 v[174:177], v168 offset:2048
	ds_read_b128 v[178:181], v168 offset:3072
	s_add_u32 s20, s18, 0x100
	s_addc_u32 s21, s19, 0
	s_cmp_eq_u32 s43, 40
	s_cselect_b32 s25, s7, s21
	s_cselect_b32 s24, s6, s20
	s_cselect_b32 s23, s17, s42
	s_cselect_b32 s22, s16, s41
	v_lshl_add_u64 v[164:165], s[18:19], 0, v[152:153]
	s_add_i32 m0, s26, 0xc000
	ds_read_b128 v[182:185], v169
	ds_read_b128 v[186:189], v169 offset:1024
	ds_read_b128 v[190:193], v169 offset:2048
	ds_read_b128 v[194:197], v169 offset:3072
	ds_read_b128 v[198:201], v169 offset:4096
	ds_read_b128 v[202:205], v169 offset:5120
	ds_read_b128 v[206:209], v169 offset:6144
	ds_read_b128 v[210:213], v169 offset:7168
	global_load_lds_dwordx4 v[164:165], off
	v_lshl_add_u64 v[164:165], s[18:19], 0, v[154:155]
	s_add_i32 m0, s26, 0xe000
	s_nop 0
	global_load_lds_dwordx4 v[164:165], off
	s_cmp_lg_u32 s96, 0
	s_cbranch_scc0 .Lz_skip_1
	s_mov_b32 s96, 0
	v_mov_b64_e32 v[0:1], 0
	v_mov_b64_e32 v[2:3], 0
	v_mov_b64_e32 v[4:5], 0
	v_mov_b64_e32 v[6:7], 0
	v_mov_b64_e32 v[8:9], 0
	v_mov_b64_e32 v[10:11], 0
	v_mov_b64_e32 v[12:13], 0
	v_mov_b64_e32 v[14:15], 0
	v_mov_b64_e32 v[16:17], 0
	v_mov_b64_e32 v[18:19], 0
	v_mov_b64_e32 v[20:21], 0
	v_mov_b64_e32 v[22:23], 0
	v_mov_b64_e32 v[24:25], 0
	v_mov_b64_e32 v[26:27], 0
	v_mov_b64_e32 v[28:29], 0
	v_mov_b64_e32 v[30:31], 0
	v_mov_b64_e32 v[32:33], 0
	v_mov_b64_e32 v[34:35], 0
	v_mov_b64_e32 v[36:37], 0
	v_mov_b64_e32 v[38:39], 0
	v_mov_b64_e32 v[40:41], 0
	v_mov_b64_e32 v[42:43], 0
	v_mov_b64_e32 v[44:45], 0
	v_mov_b64_e32 v[46:47], 0
	v_mov_b64_e32 v[48:49], 0
	v_mov_b64_e32 v[50:51], 0
	v_mov_b64_e32 v[52:53], 0
	v_mov_b64_e32 v[54:55], 0
	v_mov_b64_e32 v[56:57], 0
	v_mov_b64_e32 v[58:59], 0
	v_mov_b64_e32 v[60:61], 0
	v_mov_b64_e32 v[62:63], 0
	v_mov_b64_e32 v[64:65], 0
	v_mov_b64_e32 v[66:67], 0
	v_mov_b64_e32 v[68:69], 0
	v_mov_b64_e32 v[70:71], 0
	v_mov_b64_e32 v[72:73], 0
	v_mov_b64_e32 v[74:75], 0
	v_mov_b64_e32 v[76:77], 0
	v_mov_b64_e32 v[78:79], 0
	v_mov_b64_e32 v[80:81], 0
	v_mov_b64_e32 v[82:83], 0
	v_mov_b64_e32 v[84:85], 0
	v_mov_b64_e32 v[86:87], 0
	v_mov_b64_e32 v[88:89], 0
	v_mov_b64_e32 v[90:91], 0
	v_mov_b64_e32 v[92:93], 0
	v_mov_b64_e32 v[94:95], 0
	v_mov_b64_e32 v[96:97], 0
	v_mov_b64_e32 v[98:99], 0
	v_mov_b64_e32 v[100:101], 0
	v_mov_b64_e32 v[102:103], 0
	v_mov_b64_e32 v[104:105], 0
	v_mov_b64_e32 v[106:107], 0
	v_mov_b64_e32 v[108:109], 0
	v_mov_b64_e32 v[110:111], 0
	v_mov_b64_e32 v[112:113], 0
	v_mov_b64_e32 v[114:115], 0
	v_mov_b64_e32 v[116:117], 0
	v_mov_b64_e32 v[118:119], 0
	v_mov_b64_e32 v[120:121], 0
	v_mov_b64_e32 v[122:123], 0
	v_mov_b64_e32 v[124:125], 0
	v_mov_b64_e32 v[126:127], 0
.Lz_skip_1:
	s_waitcnt vmcnt(8)
	s_waitcnt lgkmcnt(0)
	s_barrier
	s_setprio 1
	s_waitcnt lgkmcnt(0)
	v_mfma_f32_16x16x32_bf16 v[124:127], v[128:131], v[182:185], v[124:127]
	v_mfma_f32_16x16x32_bf16 v[120:123], v[136:139], v[182:185], v[120:123]
	v_mfma_f32_16x16x32_bf16 v[116:119], v[128:131], v[190:193], v[116:119]
	v_mfma_f32_16x16x32_bf16 v[112:115], v[136:139], v[190:193], v[112:115]
	v_mfma_f32_16x16x32_bf16 v[108:111], v[128:131], v[198:201], v[108:111]
	v_mfma_f32_16x16x32_bf16 v[96:99], v[136:139], v[198:201], v[96:99]
	v_mfma_f32_16x16x32_bf16 v[80:83], v[128:131], v[206:209], v[80:83]
	v_mfma_f32_16x16x32_bf16 v[76:79], v[136:139], v[206:209], v[76:79]
	v_mfma_f32_16x16x32_bf16 v[124:127], v[132:135], v[186:189], v[124:127]
	v_mfma_f32_16x16x32_bf16 v[120:123], v[140:143], v[186:189], v[120:123]
	v_mfma_f32_16x16x32_bf16 v[116:119], v[132:135], v[194:197], v[116:119]
	v_mfma_f32_16x16x32_bf16 v[112:115], v[140:143], v[194:197], v[112:115]
	v_mfma_f32_16x16x32_bf16 v[108:111], v[132:135], v[202:205], v[108:111]
	v_mfma_f32_16x16x32_bf16 v[96:99], v[140:143], v[202:205], v[96:99]
	v_mfma_f32_16x16x32_bf16 v[80:83], v[132:135], v[210:213], v[80:83]
	v_mfma_f32_16x16x32_bf16 v[76:79], v[140:143], v[210:213], v[76:79]
	s_setprio 0
	s_setprio 1
	v_mfma_f32_16x16x32_bf16 v[104:107], v[160:163], v[182:185], v[104:107]
	v_mfma_f32_16x16x32_bf16 v[100:103], v[174:177], v[182:185], v[100:103]
	v_mfma_f32_16x16x32_bf16 v[92:95], v[160:163], v[190:193], v[92:95]
	v_mfma_f32_16x16x32_bf16 v[88:91], v[174:177], v[190:193], v[88:91]
	v_mfma_f32_16x16x32_bf16 v[84:87], v[160:163], v[198:201], v[84:87]
	v_mfma_f32_16x16x32_bf16 v[72:75], v[174:177], v[198:201], v[72:75]
	v_mfma_f32_16x16x32_bf16 v[68:71], v[160:163], v[206:209], v[68:71]
	v_mfma_f32_16x16x32_bf16 v[64:67], v[174:177], v[206:209], v[64:67]
	v_mfma_f32_16x16x32_bf16 v[104:107], v[170:173], v[186:189], v[104:107]
	v_mfma_f32_16x16x32_bf16 v[100:103], v[178:181], v[186:189], v[100:103]
	v_mfma_f32_16x16x32_bf16 v[92:95], v[170:173], v[194:197], v[92:95]
	v_mfma_f32_16x16x32_bf16 v[88:91], v[178:181], v[194:197], v[88:91]
	v_mfma_f32_16x16x32_bf16 v[84:87], v[170:173], v[202:205], v[84:87]
	v_mfma_f32_16x16x32_bf16 v[72:75], v[178:181], v[202:205], v[72:75]
	v_mfma_f32_16x16x32_bf16 v[68:71], v[170:173], v[210:213], v[68:71]
	v_mfma_f32_16x16x32_bf16 v[64:67], v[178:181], v[210:213], v[64:67]
	s_setprio 0
	s_barrier
	s_add_i32 s18, s35, s33
	v_lshl_add_u64 v[164:165], s[22:23], 0, v[146:147]
	s_mov_b32 m0, s18
	ds_read_b128 v[182:185], v169 offset:16384
	ds_read_b128 v[186:189], v169 offset:17408
	ds_read_b128 v[190:193], v169 offset:18432
	ds_read_b128 v[194:197], v169 offset:19456
	ds_read_b128 v[198:201], v169 offset:20480
	ds_read_b128 v[202:205], v169 offset:21504
	ds_read_b128 v[206:209], v169 offset:22528
	ds_read_b128 v[210:213], v169 offset:23552
	global_load_lds_dwordx4 v[164:165], off
	s_add_i32 m0, s18, 0x2000
	s_add_u32 s18, s22, 0xb0000
	v_lshl_add_u64 v[214:215], s[22:23], 0, v[150:151]
	s_addc_u32 s19, s23, 0
	s_add_i32 s46, s36, s33
	global_load_lds_dwordx4 v[214:215], off
	v_lshl_add_u64 v[216:217], s[18:19], 0, v[146:147]
	s_mov_b32 m0, s46
	v_lshl_add_u64 v[218:219], s[24:25], 0, v[148:149]
	global_load_lds_dwordx4 v[216:217], off
	v_lshl_add_u64 v[216:217], s[18:19], 0, v[150:151]
	s_add_i32 m0, s46, 0x2000
	s_nop 0
	global_load_lds_dwordx4 v[216:217], off
	v_lshl_add_u64 v[216:217], s[24:25], 0, v[144:145]
	s_mov_b32 m0, s26
	s_nop 0
	global_load_lds_dwordx4 v[216:217], off
	s_mov_b32 m0, s27
	s_nop 0
	global_load_lds_dwordx4 v[218:219], off
	s_waitcnt vmcnt(8)
	s_waitcnt lgkmcnt(0)
	s_barrier
	s_setprio 1
	s_waitcnt lgkmcnt(0)
	v_mfma_f32_16x16x32_bf16 v[60:63], v[128:131], v[182:185], v[60:63]
	v_mfma_f32_16x16x32_bf16 v[56:59], v[136:139], v[182:185], v[56:59]
	v_mfma_f32_16x16x32_bf16 v[52:55], v[128:131], v[190:193], v[52:55]
	v_mfma_f32_16x16x32_bf16 v[48:51], v[136:139], v[190:193], v[48:51]
	v_mfma_f32_16x16x32_bf16 v[44:47], v[128:131], v[198:201], v[44:47]
	v_mfma_f32_16x16x32_bf16 v[32:35], v[136:139], v[198:201], v[32:35]
	v_mfma_f32_16x16x32_bf16 v[16:19], v[128:131], v[206:209], v[16:19]
	v_mfma_f32_16x16x32_bf16 v[12:15], v[136:139], v[206:209], v[12:15]
	v_mfma_f32_16x16x32_bf16 v[60:63], v[132:135], v[186:189], v[60:63]
	v_mfma_f32_16x16x32_bf16 v[56:59], v[140:143], v[186:189], v[56:59]
	v_mfma_f32_16x16x32_bf16 v[52:55], v[132:135], v[194:197], v[52:55]
	v_mfma_f32_16x16x32_bf16 v[48:51], v[140:143], v[194:197], v[48:51]
	v_mfma_f32_16x16x32_bf16 v[44:47], v[132:135], v[202:205], v[44:47]
	v_mfma_f32_16x16x32_bf16 v[32:35], v[140:143], v[202:205], v[32:35]
	v_mfma_f32_16x16x32_bf16 v[16:19], v[132:135], v[210:213], v[16:19]
	v_mfma_f32_16x16x32_bf16 v[12:15], v[140:143], v[210:213], v[12:15]
	s_setprio 0
	s_setprio 1
	v_mfma_f32_16x16x32_bf16 v[40:43], v[160:163], v[182:185], v[40:43]
	v_mfma_f32_16x16x32_bf16 v[36:39], v[174:177], v[182:185], v[36:39]
	v_mfma_f32_16x16x32_bf16 v[28:31], v[160:163], v[190:193], v[28:31]
	v_mfma_f32_16x16x32_bf16 v[24:27], v[174:177], v[190:193], v[24:27]
	v_mfma_f32_16x16x32_bf16 v[20:23], v[160:163], v[198:201], v[20:23]
	v_mfma_f32_16x16x32_bf16 v[8:11], v[174:177], v[198:201], v[8:11]
	v_mfma_f32_16x16x32_bf16 v[4:7], v[160:163], v[206:209], v[4:7]
	v_mfma_f32_16x16x32_bf16 v[0:3], v[174:177], v[206:209], v[0:3]
	v_mfma_f32_16x16x32_bf16 v[40:43], v[170:173], v[186:189], v[40:43]
	v_mfma_f32_16x16x32_bf16 v[36:39], v[178:181], v[186:189], v[36:39]
	v_mfma_f32_16x16x32_bf16 v[28:31], v[170:173], v[194:197], v[28:31]
	v_mfma_f32_16x16x32_bf16 v[24:27], v[178:181], v[194:197], v[24:27]
	v_mfma_f32_16x16x32_bf16 v[20:23], v[170:173], v[202:205], v[20:23]
	v_mfma_f32_16x16x32_bf16 v[8:11], v[178:181], v[202:205], v[8:11]
	v_mfma_f32_16x16x32_bf16 v[4:7], v[170:173], v[210:213], v[4:7]
	v_mfma_f32_16x16x32_bf16 v[0:3], v[178:181], v[210:213], v[0:3]
	s_setprio 0
	s_barrier
	s_add_i32 s46, 0, 0x18000
	s_add_i32 s47, 0, 0x1c000
	v_add_u32_e32 v140, s46, v166
	v_add_u32_e32 v178, s47, v166
	ds_read_b128 v[128:131], v140
	ds_read_b128 v[132:135], v140 offset:1024
	ds_read_b128 v[136:139], v140 offset:2048
	ds_read_b128 v[140:143], v140 offset:3072
	ds_read_b128 v[160:163], v178
	ds_read_b128 v[170:173], v178 offset:1024
	ds_read_b128 v[174:177], v178 offset:2048
	ds_read_b128 v[178:181], v178 offset:3072
	s_add_u32 s18, s24, 0xb0000
	s_addc_u32 s19, s25, 0
	s_mov_b32 m0, s28
	v_lshl_add_u64 v[220:221], s[18:19], 0, v[144:145]
	ds_read_b128 v[182:185], v169 offset:32768
	ds_read_b128 v[186:189], v169 offset:33792
	ds_read_b128 v[190:193], v169 offset:34816
	ds_read_b128 v[194:197], v169 offset:35840
	ds_read_b128 v[198:201], v169 offset:36864
	ds_read_b128 v[202:205], v169 offset:37888
	ds_read_b128 v[206:209], v169 offset:38912
	ds_read_b128 v[210:213], v169 offset:39936
	global_load_lds_dwordx4 v[220:221], off
	v_lshl_add_u64 v[220:221], s[18:19], 0, v[148:149]
	s_mov_b32 m0, s29
	s_nop 0
	global_load_lds_dwordx4 v[220:221], off
	s_waitcnt vmcnt(8)
	s_waitcnt lgkmcnt(0)
	s_barrier
	s_setprio 1
	s_waitcnt lgkmcnt(0)
	v_mfma_f32_16x16x32_bf16 v[124:127], v[128:131], v[182:185], v[124:127]
	v_mfma_f32_16x16x32_bf16 v[120:123], v[136:139], v[182:185], v[120:123]
	v_mfma_f32_16x16x32_bf16 v[116:119], v[128:131], v[190:193], v[116:119]
	v_mfma_f32_16x16x32_bf16 v[112:115], v[136:139], v[190:193], v[112:115]
	v_mfma_f32_16x16x32_bf16 v[108:111], v[128:131], v[198:201], v[108:111]
	v_mfma_f32_16x16x32_bf16 v[96:99], v[136:139], v[198:201], v[96:99]
	v_mfma_f32_16x16x32_bf16 v[80:83], v[128:131], v[206:209], v[80:83]
	v_mfma_f32_16x16x32_bf16 v[76:79], v[136:139], v[206:209], v[76:79]
	v_mfma_f32_16x16x32_bf16 v[124:127], v[132:135], v[186:189], v[124:127]
	v_mfma_f32_16x16x32_bf16 v[120:123], v[140:143], v[186:189], v[120:123]
	v_mfma_f32_16x16x32_bf16 v[116:119], v[132:135], v[194:197], v[116:119]
	v_mfma_f32_16x16x32_bf16 v[112:115], v[140:143], v[194:197], v[112:115]
	v_mfma_f32_16x16x32_bf16 v[108:111], v[132:135], v[202:205], v[108:111]
	v_mfma_f32_16x16x32_bf16 v[96:99], v[140:143], v[202:205], v[96:99]
	v_mfma_f32_16x16x32_bf16 v[80:83], v[132:135], v[210:213], v[80:83]
	v_mfma_f32_16x16x32_bf16 v[76:79], v[140:143], v[210:213], v[76:79]
	s_setprio 0
	s_setprio 1
	v_mfma_f32_16x16x32_bf16 v[104:107], v[160:163], v[182:185], v[104:107]
	v_mfma_f32_16x16x32_bf16 v[100:103], v[174:177], v[182:185], v[100:103]
	v_mfma_f32_16x16x32_bf16 v[92:95], v[160:163], v[190:193], v[92:95]
	v_mfma_f32_16x16x32_bf16 v[88:91], v[174:177], v[190:193], v[88:91]
	v_mfma_f32_16x16x32_bf16 v[84:87], v[160:163], v[198:201], v[84:87]
	v_mfma_f32_16x16x32_bf16 v[72:75], v[174:177], v[198:201], v[72:75]
	v_mfma_f32_16x16x32_bf16 v[68:71], v[160:163], v[206:209], v[68:71]
	v_mfma_f32_16x16x32_bf16 v[64:67], v[174:177], v[206:209], v[64:67]
	v_mfma_f32_16x16x32_bf16 v[104:107], v[170:173], v[186:189], v[104:107]
	v_mfma_f32_16x16x32_bf16 v[100:103], v[178:181], v[186:189], v[100:103]
	v_mfma_f32_16x16x32_bf16 v[92:95], v[170:173], v[194:197], v[92:95]
	v_mfma_f32_16x16x32_bf16 v[88:91], v[178:181], v[194:197], v[88:91]
	v_mfma_f32_16x16x32_bf16 v[84:87], v[170:173], v[202:205], v[84:87]
	v_mfma_f32_16x16x32_bf16 v[72:75], v[178:181], v[202:205], v[72:75]
	v_mfma_f32_16x16x32_bf16 v[68:71], v[170:173], v[210:213], v[68:71]
	v_mfma_f32_16x16x32_bf16 v[64:67], v[178:181], v[210:213], v[64:67]
	s_setprio 0
	s_barrier
	s_add_i32 s18, s46, s33
	v_lshl_add_u64 v[164:165], v[164:165], 0, s[8:9]
	s_mov_b32 m0, s18
	ds_read_b128 v[182:185], v169 offset:49152
	ds_read_b128 v[186:189], v169 offset:50176
	ds_read_b128 v[190:193], v169 offset:51200
	ds_read_b128 v[194:197], v169 offset:52224
	ds_read_b128 v[198:201], v169 offset:53248
	ds_read_b128 v[202:205], v169 offset:54272
	ds_read_b128 v[206:209], v169 offset:55296
	ds_read_b128 v[210:213], v169 offset:56320
	global_load_lds_dwordx4 v[164:165], off
	s_add_i32 m0, s18, 0x2000
	s_add_u32 s18, s22, 0xb0080
	v_lshl_add_u64 v[164:165], v[214:215], 0, s[8:9]
	s_addc_u32 s19, s23, 0
	s_add_i32 s22, s47, s33
	global_load_lds_dwordx4 v[164:165], off
	v_lshl_add_u64 v[164:165], s[18:19], 0, v[146:147]
	s_mov_b32 m0, s22
	s_nop 0
	global_load_lds_dwordx4 v[164:165], off
	v_lshl_add_u64 v[164:165], s[18:19], 0, v[150:151]
	s_add_i32 m0, s22, 0x2000
	s_nop 0
	global_load_lds_dwordx4 v[164:165], off
	v_lshl_add_u64 v[164:165], v[216:217], 0, s[8:9]
	s_mov_b32 m0, s31
	s_nop 0
	global_load_lds_dwordx4 v[164:165], off
	v_lshl_add_u64 v[164:165], v[218:219], 0, s[8:9]
	s_mov_b32 m0, s34
	s_nop 0
	global_load_lds_dwordx4 v[164:165], off
	s_waitcnt vmcnt(8)
	s_waitcnt lgkmcnt(0)
	s_barrier
	s_setprio 1
	s_waitcnt lgkmcnt(0)
	v_mfma_f32_16x16x32_bf16 v[60:63], v[128:131], v[182:185], v[60:63]
	v_mfma_f32_16x16x32_bf16 v[56:59], v[136:139], v[182:185], v[56:59]
	v_mfma_f32_16x16x32_bf16 v[52:55], v[128:131], v[190:193], v[52:55]
	v_mfma_f32_16x16x32_bf16 v[48:51], v[136:139], v[190:193], v[48:51]
	v_mfma_f32_16x16x32_bf16 v[44:47], v[128:131], v[198:201], v[44:47]
	v_mfma_f32_16x16x32_bf16 v[32:35], v[136:139], v[198:201], v[32:35]
	v_mfma_f32_16x16x32_bf16 v[16:19], v[128:131], v[206:209], v[16:19]
	v_mfma_f32_16x16x32_bf16 v[12:15], v[136:139], v[206:209], v[12:15]
	v_mfma_f32_16x16x32_bf16 v[60:63], v[132:135], v[186:189], v[60:63]
	v_mfma_f32_16x16x32_bf16 v[56:59], v[140:143], v[186:189], v[56:59]
	v_mfma_f32_16x16x32_bf16 v[52:55], v[132:135], v[194:197], v[52:55]
	v_mfma_f32_16x16x32_bf16 v[48:51], v[140:143], v[194:197], v[48:51]
	v_mfma_f32_16x16x32_bf16 v[44:47], v[132:135], v[202:205], v[44:47]
	v_mfma_f32_16x16x32_bf16 v[32:35], v[140:143], v[202:205], v[32:35]
	v_mfma_f32_16x16x32_bf16 v[16:19], v[132:135], v[210:213], v[16:19]
	v_mfma_f32_16x16x32_bf16 v[12:15], v[140:143], v[210:213], v[12:15]
	s_setprio 0
	s_setprio 1
	v_mfma_f32_16x16x32_bf16 v[40:43], v[160:163], v[182:185], v[40:43]
	v_mfma_f32_16x16x32_bf16 v[36:39], v[174:177], v[182:185], v[36:39]
	v_mfma_f32_16x16x32_bf16 v[28:31], v[160:163], v[190:193], v[28:31]
	v_mfma_f32_16x16x32_bf16 v[24:27], v[174:177], v[190:193], v[24:27]
	v_mfma_f32_16x16x32_bf16 v[20:23], v[160:163], v[198:201], v[20:23]
	v_mfma_f32_16x16x32_bf16 v[8:11], v[174:177], v[198:201], v[8:11]
	v_mfma_f32_16x16x32_bf16 v[4:7], v[160:163], v[206:209], v[4:7]
	v_mfma_f32_16x16x32_bf16 v[0:3], v[174:177], v[206:209], v[0:3]
	v_mfma_f32_16x16x32_bf16 v[40:43], v[170:173], v[186:189], v[40:43]
	v_mfma_f32_16x16x32_bf16 v[36:39], v[178:181], v[186:189], v[36:39]
	v_mfma_f32_16x16x32_bf16 v[28:31], v[170:173], v[194:197], v[28:31]
	v_mfma_f32_16x16x32_bf16 v[24:27], v[178:181], v[194:197], v[24:27]
	v_mfma_f32_16x16x32_bf16 v[20:23], v[170:173], v[202:205], v[20:23]
	v_mfma_f32_16x16x32_bf16 v[8:11], v[178:181], v[202:205], v[8:11]
	v_mfma_f32_16x16x32_bf16 v[4:7], v[170:173], v[210:213], v[4:7]
	v_mfma_f32_16x16x32_bf16 v[0:3], v[178:181], v[210:213], v[0:3]
	s_setprio 0
	s_barrier
	s_add_i32 s43, s43, 2
	s_add_u32 s41, s41, 0x100
	s_addc_u32 s42, s42, 0
	s_cmp_gt_u32 s43, 41
	s_mov_b64 s[18:19], s[20:21]
	s_cbranch_scc0 .LBB0_1184
	v_readlane_b32 s18, v255, 4
	v_readlane_b32 s19, v255, 5
	s_and_b64 vcc, exec, s[18:19]
	s_cbranch_vccz .LBB0_1187
	s_barrier

.LBB0_1270:
	s_add_u32 s7, s34, 0x100
	v_mov_b32_e32 v0, 0
	s_addc_u32 s29, s35, 0
	s_mov_b32 s54, -2
	s_mov_b32 s96, 1
.LBB0_1271:
	ds_read_b128 v[128:131], v192
	ds_read_b128 v[132:135], v192 offset:1024
	ds_read_b128 v[136:139], v192 offset:2048
	ds_read_b128 v[140:143], v192 offset:3072
	ds_read_b128 v[160:163], v193
	ds_read_b128 v[164:167], v193 offset:1024
	ds_read_b128 v[168:171], v193 offset:2048
	ds_read_b128 v[172:175], v193 offset:3072
	s_add_u32 s4, s30, 0x100
	s_addc_u32 s5, s31, 0
	s_cmp_eq_u32 s54, 40
	s_cselect_b32 s37, s25, s5
	s_cselect_b32 s36, s24, s4
	s_cselect_b32 s35, s27, s29
	s_cselect_b32 s34, s26, s7
	v_lshl_add_u64 v[156:157], s[30:31], 0, v[152:153]
	s_add_i32 m0, s38, 0xc000
	ds_read_b128 v[176:179], v194
	ds_read_b128 v[180:183], v194 offset:1024
	ds_read_b128 v[184:187], v194 offset:2048
	ds_read_b128 v[198:201], v194 offset:3072
	ds_read_b128 v[202:205], v194 offset:4096
	ds_read_b128 v[206:209], v194 offset:5120
	ds_read_b128 v[210:213], v194 offset:6144
	ds_read_b128 v[214:217], v194 offset:7168
	global_load_lds_dwordx4 v[156:157], off
	v_lshl_add_u64 v[156:157], s[30:31], 0, v[154:155]
	s_add_i32 m0, s38, 0xe000
	s_nop 0
	global_load_lds_dwordx4 v[156:157], off
	s_cmp_lg_u32 s96, 0
	s_cbranch_scc0 .Lz_skip_0
	s_mov_b32 s96, 0
	v_mov_b64_e32 v[0:1], 0
	v_mov_b64_e32 v[2:3], 0
	v_mov_b64_e32 v[4:5], 0
	v_mov_b64_e32 v[6:7], 0
	v_mov_b64_e32 v[8:9], 0
	v_mov_b64_e32 v[10:11], 0
	v_mov_b64_e32 v[12:13], 0
	v_mov_b64_e32 v[14:15], 0
	v_mov_b64_e32 v[16:17], 0
	v_mov_b64_e32 v[18:19], 0
	v_mov_b64_e32 v[20:21], 0
	v_mov_b64_e32 v[22:23], 0
	v_mov_b64_e32 v[24:25], 0
	v_mov_b64_e32 v[26:27], 0
	v_mov_b64_e32 v[28:29], 0
	v_mov_b64_e32 v[30:31], 0
	v_mov_b64_e32 v[32:33], 0
	v_mov_b64_e32 v[34:35], 0
	v_mov_b64_e32 v[36:37], 0
	v_mov_b64_e32 v[38:39], 0
	v_mov_b64_e32 v[40:41], 0
	v_mov_b64_e32 v[42:43], 0
	v_mov_b64_e32 v[44:45], 0
	v_mov_b64_e32 v[46:47], 0
	v_mov_b64_e32 v[48:49], 0
	v_mov_b64_e32 v[50:51], 0
	v_mov_b64_e32 v[52:53], 0
	v_mov_b64_e32 v[54:55], 0
	v_mov_b64_e32 v[56:57], 0
	v_mov_b64_e32 v[58:59], 0
	v_mov_b64_e32 v[60:61], 0
	v_mov_b64_e32 v[62:63], 0
	v_mov_b64_e32 v[64:65], 0
	v_mov_b64_e32 v[66:67], 0
	v_mov_b64_e32 v[68:69], 0
	v_mov_b64_e32 v[70:71], 0
	v_mov_b64_e32 v[72:73], 0
	v_mov_b64_e32 v[74:75], 0
	v_mov_b64_e32 v[76:77], 0
	v_mov_b64_e32 v[78:79], 0
	v_mov_b64_e32 v[80:81], 0
	v_mov_b64_e32 v[82:83], 0
	v_mov_b64_e32 v[84:85], 0
	v_mov_b64_e32 v[86:87], 0
	v_mov_b64_e32 v[88:89], 0
	v_mov_b64_e32 v[90:91], 0
	v_mov_b64_e32 v[92:93], 0
	v_mov_b64_e32 v[94:95], 0
	v_mov_b64_e32 v[96:97], 0
	v_mov_b64_e32 v[98:99], 0
	v_mov_b64_e32 v[100:101], 0
	v_mov_b64_e32 v[102:103], 0
	v_mov_b64_e32 v[104:105], 0
	v_mov_b64_e32 v[106:107], 0
	v_mov_b64_e32 v[108:109], 0
	v_mov_b64_e32 v[110:111], 0
	v_mov_b64_e32 v[112:113], 0
	v_mov_b64_e32 v[114:115], 0
	v_mov_b64_e32 v[116:117], 0
	v_mov_b64_e32 v[118:119], 0
	v_mov_b64_e32 v[120:121], 0
	v_mov_b64_e32 v[122:123], 0
	v_mov_b64_e32 v[124:125], 0
	v_mov_b64_e32 v[126:127], 0
.Lz_skip_0:
	s_waitcnt vmcnt(8)
	s_waitcnt lgkmcnt(0)
	s_barrier
	s_setprio 1
	s_waitcnt lgkmcnt(0)
	v_mfma_f32_16x16x32_bf16 v[124:127], v[128:131], v[176:179], v[124:127]
	v_mfma_f32_16x16x32_bf16 v[120:123], v[136:139], v[176:179], v[120:123]
	v_mfma_f32_16x16x32_bf16 v[112:115], v[128:131], v[184:187], v[112:115]
	v_mfma_f32_16x16x32_bf16 v[104:107], v[136:139], v[184:187], v[104:107]
	v_mfma_f32_16x16x32_bf16 v[92:95], v[128:131], v[202:205], v[92:95]
	v_mfma_f32_16x16x32_bf16 v[88:91], v[136:139], v[202:205], v[88:91]
	v_mfma_f32_16x16x32_bf16 v[84:87], v[128:131], v[210:213], v[84:87]
	v_mfma_f32_16x16x32_bf16 v[80:83], v[136:139], v[210:213], v[80:83]
	v_mfma_f32_16x16x32_bf16 v[124:127], v[132:135], v[180:183], v[124:127]
	v_mfma_f32_16x16x32_bf16 v[120:123], v[140:143], v[180:183], v[120:123]
	v_mfma_f32_16x16x32_bf16 v[112:115], v[132:135], v[198:201], v[112:115]
	v_mfma_f32_16x16x32_bf16 v[104:107], v[140:143], v[198:201], v[104:107]
	v_mfma_f32_16x16x32_bf16 v[92:95], v[132:135], v[206:209], v[92:95]
	v_mfma_f32_16x16x32_bf16 v[88:91], v[140:143], v[206:209], v[88:91]
	v_mfma_f32_16x16x32_bf16 v[84:87], v[132:135], v[214:217], v[84:87]
	v_mfma_f32_16x16x32_bf16 v[80:83], v[140:143], v[214:217], v[80:83]
	s_setprio 0
	s_setprio 1
	v_mfma_f32_16x16x32_bf16 v[116:119], v[160:163], v[176:179], v[116:119]
	v_mfma_f32_16x16x32_bf16 v[108:111], v[168:171], v[176:179], v[108:111]
	v_mfma_f32_16x16x32_bf16 v[100:103], v[160:163], v[184:187], v[100:103]
	v_mfma_f32_16x16x32_bf16 v[96:99], v[168:171], v[184:187], v[96:99]
	v_mfma_f32_16x16x32_bf16 v[76:79], v[160:163], v[202:205], v[76:79]
	v_mfma_f32_16x16x32_bf16 v[72:75], v[168:171], v[202:205], v[72:75]
	v_mfma_f32_16x16x32_bf16 v[68:71], v[160:163], v[210:213], v[68:71]
	v_mfma_f32_16x16x32_bf16 v[64:67], v[168:171], v[210:213], v[64:67]
	v_mfma_f32_16x16x32_bf16 v[116:119], v[164:167], v[180:183], v[116:119]
	v_mfma_f32_16x16x32_bf16 v[108:111], v[172:175], v[180:183], v[108:111]
	v_mfma_f32_16x16x32_bf16 v[100:103], v[164:167], v[198:201], v[100:103]
	v_mfma_f32_16x16x32_bf16 v[96:99], v[172:175], v[198:201], v[96:99]
	v_mfma_f32_16x16x32_bf16 v[76:79], v[164:167], v[206:209], v[76:79]
	v_mfma_f32_16x16x32_bf16 v[72:75], v[172:175], v[206:209], v[72:75]
	v_mfma_f32_16x16x32_bf16 v[68:71], v[164:167], v[214:217], v[68:71]
	v_mfma_f32_16x16x32_bf16 v[64:67], v[172:175], v[214:217], v[64:67]
	s_setprio 0
	s_barrier
	s_add_i32 s30, s48, s33
	v_lshl_add_u64 v[156:157], s[34:35], 0, v[146:147]
	s_mov_b32 m0, s30
	ds_read_b128 v[176:179], v194 offset:16384
	ds_read_b128 v[180:183], v194 offset:17408
	ds_read_b128 v[184:187], v194 offset:18432
	ds_read_b128 v[198:201], v194 offset:19456
	ds_read_b128 v[202:205], v194 offset:20480
	ds_read_b128 v[206:209], v194 offset:21504
	ds_read_b128 v[210:213], v194 offset:22528
	ds_read_b128 v[214:217], v194 offset:23552
	global_load_lds_dwordx4 v[156:157], off
	s_add_i32 m0, s30, 0x2000
	s_add_u32 s30, s34, 0xb0000
	v_lshl_add_u64 v[158:159], s[34:35], 0, v[150:151]
	s_addc_u32 s31, s35, 0
	s_add_i32 s55, s49, s33
	global_load_lds_dwordx4 v[158:159], off
	v_lshl_add_u64 v[188:189], s[30:31], 0, v[146:147]
	s_mov_b32 m0, s55
	v_lshl_add_u64 v[218:219], s[36:37], 0, v[148:149]
	global_load_lds_dwordx4 v[188:189], off
	v_lshl_add_u64 v[188:189], s[30:31], 0, v[150:151]
	s_add_i32 m0, s55, 0x2000
	s_nop 0
	global_load_lds_dwordx4 v[188:189], off
	v_lshl_add_u64 v[188:189], s[36:37], 0, v[144:145]
	s_mov_b32 m0, s38
	s_nop 0
	global_load_lds_dwordx4 v[188:189], off
	s_mov_b32 m0, s39
	s_nop 0
	global_load_lds_dwordx4 v[218:219], off
	s_waitcnt vmcnt(8)
	s_waitcnt lgkmcnt(0)
	s_barrier
	s_setprio 1
	s_waitcnt lgkmcnt(0)
	v_mfma_f32_16x16x32_bf16 v[60:63], v[128:131], v[176:179], v[60:63]
	v_mfma_f32_16x16x32_bf16 v[56:59], v[136:139], v[176:179], v[56:59]
	v_mfma_f32_16x16x32_bf16 v[48:51], v[128:131], v[184:187], v[48:51]
	v_mfma_f32_16x16x32_bf16 v[40:43], v[136:139], v[184:187], v[40:43]
	v_mfma_f32_16x16x32_bf16 v[36:39], v[128:131], v[202:205], v[36:39]
	v_mfma_f32_16x16x32_bf16 v[24:27], v[136:139], v[202:205], v[24:27]
	v_mfma_f32_16x16x32_bf16 v[16:19], v[128:131], v[210:213], v[16:19]
	v_mfma_f32_16x16x32_bf16 v[8:11], v[136:139], v[210:213], v[8:11]
	v_mfma_f32_16x16x32_bf16 v[60:63], v[132:135], v[180:183], v[60:63]
	v_mfma_f32_16x16x32_bf16 v[56:59], v[140:143], v[180:183], v[56:59]
	v_mfma_f32_16x16x32_bf16 v[48:51], v[132:135], v[198:201], v[48:51]
	v_mfma_f32_16x16x32_bf16 v[40:43], v[140:143], v[198:201], v[40:43]
	v_mfma_f32_16x16x32_bf16 v[36:39], v[132:135], v[206:209], v[36:39]
	v_mfma_f32_16x16x32_bf16 v[24:27], v[140:143], v[206:209], v[24:27]
	v_mfma_f32_16x16x32_bf16 v[16:19], v[132:135], v[214:217], v[16:19]
	v_mfma_f32_16x16x32_bf16 v[8:11], v[140:143], v[214:217], v[8:11]
	s_setprio 0
	s_setprio 1
	v_mfma_f32_16x16x32_bf16 v[52:55], v[160:163], v[176:179], v[52:55]
	v_mfma_f32_16x16x32_bf16 v[44:47], v[168:171], v[176:179], v[44:47]
	v_mfma_f32_16x16x32_bf16 v[32:35], v[160:163], v[184:187], v[32:35]
	v_mfma_f32_16x16x32_bf16 v[28:31], v[168:171], v[184:187], v[28:31]
	v_mfma_f32_16x16x32_bf16 v[20:23], v[160:163], v[202:205], v[20:23]
	v_mfma_f32_16x16x32_bf16 v[12:15], v[168:171], v[202:205], v[12:15]
	v_mfma_f32_16x16x32_bf16 v[4:7], v[160:163], v[210:213], v[4:7]
	v_mfma_f32_16x16x32_bf16 v[0:3], v[168:171], v[210:213], v[0:3]
	v_mfma_f32_16x16x32_bf16 v[52:55], v[164:167], v[180:183], v[52:55]
	v_mfma_f32_16x16x32_bf16 v[44:47], v[172:175], v[180:183], v[44:47]
	v_mfma_f32_16x16x32_bf16 v[32:35], v[164:167], v[198:201], v[32:35]
	v_mfma_f32_16x16x32_bf16 v[28:31], v[172:175], v[198:201], v[28:31]
	v_mfma_f32_16x16x32_bf16 v[20:23], v[164:167], v[206:209], v[20:23]
	v_mfma_f32_16x16x32_bf16 v[12:15], v[172:175], v[206:209], v[12:15]
	v_mfma_f32_16x16x32_bf16 v[4:7], v[164:167], v[214:217], v[4:7]
	v_mfma_f32_16x16x32_bf16 v[0:3], v[172:175], v[214:217], v[0:3]
	s_setprio 0
	s_barrier
	s_add_i32 s55, 0, 0x18000
	s_add_i32 s56, 0, 0x1c000
	v_add_u32_e32 v140, s55, v191
	v_add_u32_e32 v172, s56, v191
	ds_read_b128 v[128:131], v140
	ds_read_b128 v[132:135], v140 offset:1024
	ds_read_b128 v[136:139], v140 offset:2048
	ds_read_b128 v[140:143], v140 offset:3072
	ds_read_b128 v[160:163], v172
	ds_read_b128 v[164:167], v172 offset:1024
	ds_read_b128 v[168:171], v172 offset:2048
	ds_read_b128 v[172:175], v172 offset:3072
	s_add_u32 s30, s36, 0xb0000
	s_addc_u32 s31, s37, 0
	s_mov_b32 m0, s40
	v_lshl_add_u64 v[220:221], s[30:31], 0, v[144:145]
	ds_read_b128 v[176:179], v194 offset:32768
	ds_read_b128 v[180:183], v194 offset:33792
	ds_read_b128 v[184:187], v194 offset:34816
	ds_read_b128 v[198:201], v194 offset:35840
	ds_read_b128 v[202:205], v194 offset:36864
	ds_read_b128 v[206:209], v194 offset:37888
	ds_read_b128 v[210:213], v194 offset:38912
	ds_read_b128 v[214:217], v194 offset:39936
	global_load_lds_dwordx4 v[220:221], off
	v_lshl_add_u64 v[220:221], s[30:31], 0, v[148:149]
	s_mov_b32 m0, s41
	s_nop 0
	global_load_lds_dwordx4 v[220:221], off
	s_waitcnt vmcnt(8)
	s_waitcnt lgkmcnt(0)
	s_barrier
	s_setprio 1
	s_waitcnt lgkmcnt(0)
	v_mfma_f32_16x16x32_bf16 v[124:127], v[128:131], v[176:179], v[124:127]
	v_mfma_f32_16x16x32_bf16 v[120:123], v[136:139], v[176:179], v[120:123]
	v_mfma_f32_16x16x32_bf16 v[112:115], v[128:131], v[184:187], v[112:115]
	v_mfma_f32_16x16x32_bf16 v[104:107], v[136:139], v[184:187], v[104:107]
	v_mfma_f32_16x16x32_bf16 v[92:95], v[128:131], v[202:205], v[92:95]
	v_mfma_f32_16x16x32_bf16 v[88:91], v[136:139], v[202:205], v[88:91]
	v_mfma_f32_16x16x32_bf16 v[84:87], v[128:131], v[210:213], v[84:87]
	v_mfma_f32_16x16x32_bf16 v[80:83], v[136:139], v[210:213], v[80:83]
	v_mfma_f32_16x16x32_bf16 v[124:127], v[132:135], v[180:183], v[124:127]
	v_mfma_f32_16x16x32_bf16 v[120:123], v[140:143], v[180:183], v[120:123]
	v_mfma_f32_16x16x32_bf16 v[112:115], v[132:135], v[198:201], v[112:115]
	v_mfma_f32_16x16x32_bf16 v[104:107], v[140:143], v[198:201], v[104:107]
	v_mfma_f32_16x16x32_bf16 v[92:95], v[132:135], v[206:209], v[92:95]
	v_mfma_f32_16x16x32_bf16 v[88:91], v[140:143], v[206:209], v[88:91]
	v_mfma_f32_16x16x32_bf16 v[84:87], v[132:135], v[214:217], v[84:87]
	v_mfma_f32_16x16x32_bf16 v[80:83], v[140:143], v[214:217], v[80:83]
	s_setprio 0
	s_setprio 1
	v_mfma_f32_16x16x32_bf16 v[116:119], v[160:163], v[176:179], v[116:119]
	v_mfma_f32_16x16x32_bf16 v[108:111], v[168:171], v[176:179], v[108:111]
	v_mfma_f32_16x16x32_bf16 v[100:103], v[160:163], v[184:187], v[100:103]
	v_mfma_f32_16x16x32_bf16 v[96:99], v[168:171], v[184:187], v[96:99]
	v_mfma_f32_16x16x32_bf16 v[76:79], v[160:163], v[202:205], v[76:79]
	v_mfma_f32_16x16x32_bf16 v[72:75], v[168:171], v[202:205], v[72:75]
	v_mfma_f32_16x16x32_bf16 v[68:71], v[160:163], v[210:213], v[68:71]
	v_mfma_f32_16x16x32_bf16 v[64:67], v[168:171], v[210:213], v[64:67]
	v_mfma_f32_16x16x32_bf16 v[116:119], v[164:167], v[180:183], v[116:119]
	v_mfma_f32_16x16x32_bf16 v[108:111], v[172:175], v[180:183], v[108:111]
	v_mfma_f32_16x16x32_bf16 v[100:103], v[164:167], v[198:201], v[100:103]
	v_mfma_f32_16x16x32_bf16 v[96:99], v[172:175], v[198:201], v[96:99]
	v_mfma_f32_16x16x32_bf16 v[76:79], v[164:167], v[206:209], v[76:79]
	v_mfma_f32_16x16x32_bf16 v[72:75], v[172:175], v[206:209], v[72:75]
	v_mfma_f32_16x16x32_bf16 v[68:71], v[164:167], v[214:217], v[68:71]
	v_mfma_f32_16x16x32_bf16 v[64:67], v[172:175], v[214:217], v[64:67]
	s_setprio 0
	s_barrier
	s_add_i32 s30, s55, s33
	v_lshl_add_u64 v[156:157], v[156:157], 0, s[14:15]
	s_mov_b32 m0, s30
	ds_read_b128 v[176:179], v194 offset:49152
	ds_read_b128 v[180:183], v194 offset:50176
	ds_read_b128 v[184:187], v194 offset:51200
	ds_read_b128 v[198:201], v194 offset:52224
	ds_read_b128 v[202:205], v194 offset:53248
	ds_read_b128 v[206:209], v194 offset:54272
	ds_read_b128 v[210:213], v194 offset:55296
	ds_read_b128 v[214:217], v194 offset:56320
	global_load_lds_dwordx4 v[156:157], off
	s_add_i32 m0, s30, 0x2000
	s_add_u32 s30, s34, 0xb0080
	v_lshl_add_u64 v[156:157], v[158:159], 0, s[14:15]
	s_addc_u32 s31, s35, 0
	s_add_i32 s34, s56, s33
	global_load_lds_dwordx4 v[156:157], off
	v_lshl_add_u64 v[156:157], s[30:31], 0, v[146:147]
	s_mov_b32 m0, s34
	s_nop 0
	global_load_lds_dwordx4 v[156:157], off
	v_lshl_add_u64 v[156:157], s[30:31], 0, v[150:151]
	s_add_i32 m0, s34, 0x2000
	s_nop 0
	global_load_lds_dwordx4 v[156:157], off
	v_lshl_add_u64 v[156:157], v[188:189], 0, s[14:15]
	s_mov_b32 m0, s42
	s_nop 0
	global_load_lds_dwordx4 v[156:157], off
	v_lshl_add_u64 v[156:157], v[218:219], 0, s[14:15]
	s_mov_b32 m0, s43
	s_nop 0
	global_load_lds_dwordx4 v[156:157], off
	s_waitcnt vmcnt(8)
	s_waitcnt lgkmcnt(0)
	s_barrier
	s_setprio 1
	s_waitcnt lgkmcnt(0)
	v_mfma_f32_16x16x32_bf16 v[60:63], v[128:131], v[176:179], v[60:63]
	v_mfma_f32_16x16x32_bf16 v[56:59], v[136:139], v[176:179], v[56:59]
	v_mfma_f32_16x16x32_bf16 v[48:51], v[128:131], v[184:187], v[48:51]
	v_mfma_f32_16x16x32_bf16 v[40:43], v[136:139], v[184:187], v[40:43]
	v_mfma_f32_16x16x32_bf16 v[36:39], v[128:131], v[202:205], v[36:39]
	v_mfma_f32_16x16x32_bf16 v[24:27], v[136:139], v[202:205], v[24:27]
	v_mfma_f32_16x16x32_bf16 v[16:19], v[128:131], v[210:213], v[16:19]
	v_mfma_f32_16x16x32_bf16 v[8:11], v[136:139], v[210:213], v[8:11]
	v_mfma_f32_16x16x32_bf16 v[60:63], v[132:135], v[180:183], v[60:63]
	v_mfma_f32_16x16x32_bf16 v[56:59], v[140:143], v[180:183], v[56:59]
	v_mfma_f32_16x16x32_bf16 v[48:51], v[132:135], v[198:201], v[48:51]
	v_mfma_f32_16x16x32_bf16 v[40:43], v[140:143], v[198:201], v[40:43]
	v_mfma_f32_16x16x32_bf16 v[36:39], v[132:135], v[206:209], v[36:39]
	v_mfma_f32_16x16x32_bf16 v[24:27], v[140:143], v[206:209], v[24:27]
	v_mfma_f32_16x16x32_bf16 v[16:19], v[132:135], v[214:217], v[16:19]
	v_mfma_f32_16x16x32_bf16 v[8:11], v[140:143], v[214:217], v[8:11]
	s_setprio 0
	s_setprio 1
	v_mfma_f32_16x16x32_bf16 v[52:55], v[160:163], v[176:179], v[52:55]
	v_mfma_f32_16x16x32_bf16 v[44:47], v[168:171], v[176:179], v[44:47]
	v_mfma_f32_16x16x32_bf16 v[32:35], v[160:163], v[184:187], v[32:35]
	v_mfma_f32_16x16x32_bf16 v[28:31], v[168:171], v[184:187], v[28:31]
	v_mfma_f32_16x16x32_bf16 v[20:23], v[160:163], v[202:205], v[20:23]
	v_mfma_f32_16x16x32_bf16 v[12:15], v[168:171], v[202:205], v[12:15]
	v_mfma_f32_16x16x32_bf16 v[4:7], v[160:163], v[210:213], v[4:7]
	v_mfma_f32_16x16x32_bf16 v[0:3], v[168:171], v[210:213], v[0:3]
	v_mfma_f32_16x16x32_bf16 v[52:55], v[164:167], v[180:183], v[52:55]
	v_mfma_f32_16x16x32_bf16 v[44:47], v[172:175], v[180:183], v[44:47]
	v_mfma_f32_16x16x32_bf16 v[32:35], v[164:167], v[198:201], v[32:35]
	v_mfma_f32_16x16x32_bf16 v[28:31], v[172:175], v[198:201], v[28:31]
	v_mfma_f32_16x16x32_bf16 v[20:23], v[164:167], v[206:209], v[20:23]
	v_mfma_f32_16x16x32_bf16 v[12:15], v[172:175], v[206:209], v[12:15]
	v_mfma_f32_16x16x32_bf16 v[4:7], v[164:167], v[214:217], v[4:7]
	v_mfma_f32_16x16x32_bf16 v[0:3], v[172:175], v[214:217], v[0:3]
	s_setprio 0
	s_barrier
	s_add_i32 s54, s54, 2
	s_add_u32 s7, s7, 0x100
	s_addc_u32 s29, s29, 0
	s_cmp_gt_u32 s54, 41
	s_mov_b64 s[30:31], s[4:5]
	s_cbranch_scc0 .LBB0_1271
	v_readlane_b32 s4, v255, 4
	v_readlane_b32 s5, v255, 5
	s_and_b64 vcc, exec, s[4:5]
	s_cbranch_vccz .LBB0_1274
	s_barrier
